# speedup vs baseline: 1.0126x; 1.0064x over previous
; #define LAS __attribute__((address_space(3)))
; DI void ssm_prompt_unit(LAS unsigned char* lds, int unit, int tid, int l, const bf16_t* U, const bf16_t* mats_l, const float* lam16_l, bf16_t* Z, float* outr_l, float* outi_l) {
;     ...
;     bf16x8 bfr[16];
;     {
;         const bf16_t* bp = mats + 65536 + (size_t)((wave & 3) * 32 + l32) * 256 + 8 * h;
; #pragma unroll
;         for (int ks = 0; ks < 16; ++ks) bfr[ks] = *(const bf16x8*)(bp + 16 * ks);
;     }
;     u32x4 uv[8];
; #pragma unroll
;     for (int i = 0; i < 8; ++i) { const int idx = tid + i * NTHREADS, t = idx >> 1, half = idx & 1; uv[i] = *(const u32x4*)(U + (size_t)(b * SEQ + t) * SW + g * 16 + 8 * half); }
;     __syncthreads();
; #pragma unroll
;     for (int i = 0; i < 8; ++i) { const int idx = tid + i * NTHREADS, t = idx >> 1, half = idx & 1; *(LAS u32x4*)(lds + (t >> 4) * UP_PITCH + ((t & 15) * 16 + 8 * half) * 2) = uv[i]; }
;     if (tid < 64) *(LAS unsigned*)(lds + SH_OFF + tid * 4) = 0u;
;     __syncthreads();
.LBB0_399:
	s_and_b32 s6, s48, 63
	s_lshl_b32 s7, s6, 18
	s_add_u32 s52, s56, s7
	s_addc_u32 s53, s57, 0
	v_mov_b32_e32 v173, v161
	v_lshl_add_u64 v[0:1], s[52:53], 0, v[172:173]
	v_lshl_add_u64 v[0:1], v[0:1], 0, v[160:161]
	s_mov_b64 s[14:15], 0x20000
	v_lshl_add_u64 v[48:49], v[0:1], 0, s[14:15]
	global_load_dwordx4 v[88:91], v[48:49], off offset:32
	global_load_dwordx4 v[84:87], v[48:49], off offset:64
	global_load_dwordx4 v[80:83], v[48:49], off offset:96
	global_load_dwordx4 v[76:79], v[48:49], off offset:128
	global_load_dwordx4 v[72:75], v[48:49], off offset:160
	global_load_dwordx4 v[68:71], v[48:49], off offset:192
	global_load_dwordx4 v[64:67], v[48:49], off offset:224
	global_load_dwordx4 v[60:63], v[48:49], off offset:256
	global_load_dwordx4 v[56:59], v[48:49], off offset:288
	global_load_dwordx4 v[52:55], v[48:49], off offset:320
	global_load_dwordx4 v[44:47], v[48:49], off offset:352
	global_load_dwordx4 v[40:43], v[48:49], off offset:384
	global_load_dwordx4 v[36:39], v[48:49], off offset:416
	global_load_dwordx4 v[32:35], v[48:49], off offset:448
	s_lshl_b32 s7, s48, 5
	s_and_b32 s58, s7, 0xfffff800
	v_add_u32_e32 v4, s58, v174
	v_add_u32_e32 v6, s58, v175
	v_add_u32_e32 v12, s58, v176
	v_add_u32_e32 v14, s58, v177
	v_add_u32_e32 v20, s58, v178
	v_add_u32_e32 v22, s58, v179
	s_lshl_b32 s18, s6, 5
	v_ashrrev_i32_e32 v5, 31, v4
	v_ashrrev_i32_e32 v7, 31, v6
	v_ashrrev_i32_e32 v13, 31, v12
	v_ashrrev_i32_e32 v15, 31, v14
	v_ashrrev_i32_e32 v21, 31, v20
	v_ashrrev_i32_e32 v23, 31, v22
	v_lshl_add_u64 v[2:3], v[158:159], 0, s[18:19]
	v_lshlrev_b64 v[4:5], 11, v[4:5]
	v_lshlrev_b64 v[6:7], 11, v[6:7]
	v_lshlrev_b64 v[12:13], 11, v[12:13]
	v_lshlrev_b64 v[14:15], 11, v[14:15]
	v_lshlrev_b64 v[20:21], 11, v[20:21]
	v_lshlrev_b64 v[22:23], 11, v[22:23]
	v_add_u32_e32 v28, s58, v180
	v_add_u32_e32 v30, s58, v181
	v_lshl_add_u64 v[4:5], v[2:3], 0, v[4:5]
	v_lshl_add_u64 v[8:9], v[2:3], 0, v[6:7]
	v_lshl_add_u64 v[12:13], v[2:3], 0, v[12:13]
	v_lshl_add_u64 v[16:17], v[2:3], 0, v[14:15]
	v_lshl_add_u64 v[20:21], v[2:3], 0, v[20:21]
	v_lshl_add_u64 v[24:25], v[2:3], 0, v[22:23]
	v_ashrrev_i32_e32 v29, 31, v28
	v_ashrrev_i32_e32 v31, 31, v30
	v_add_co_u32_e32 v0, vcc, 0x20000, v0
	global_load_dwordx4 v[4:7], v[4:5], off
	s_nop 0
	global_load_dwordx4 v[8:11], v[8:9], off
	s_nop 0
	global_load_dwordx4 v[12:15], v[12:13], off
	s_nop 0
	global_load_dwordx4 v[16:19], v[16:17], off
	s_nop 0
	global_load_dwordx4 v[20:23], v[20:21], off
	s_nop 0
	global_load_dwordx4 v[24:27], v[24:25], off
	v_lshlrev_b64 v[28:29], 11, v[28:29]
	v_lshlrev_b64 v[30:31], 11, v[30:31]
	v_addc_co_u32_e32 v1, vcc, 0, v1, vcc
	v_lshl_add_u64 v[28:29], v[2:3], 0, v[28:29]
	v_lshl_add_u64 v[2:3], v[2:3], 0, v[30:31]
	global_load_dwordx4 v[28:31], v[28:29], off
	s_nop 0
	global_load_dwordx4 v[92:95], v[2:3], off
	s_nop 0
	global_load_dwordx4 v[0:3], v[0:1], off
	s_nop 0
	global_load_dwordx4 v[48:51], v[48:49], off offset:480
	s_barrier
	s_waitcnt vmcnt(9)
	ds_write_b128 v184, v[4:7]
	s_waitcnt vmcnt(8)
	ds_write_b128 v185, v[8:11]
	s_waitcnt vmcnt(7)
	ds_write_b128 v186, v[12:15]
	s_waitcnt vmcnt(6)
	ds_write_b128 v187, v[16:19]
	s_waitcnt vmcnt(5)
	ds_write_b128 v188, v[20:23]
	s_waitcnt vmcnt(4)
	ds_write_b128 v189, v[24:27]
	s_waitcnt vmcnt(3)
	ds_write_b128 v190, v[28:31]
	s_waitcnt vmcnt(2)
	ds_write_b128 v191, v[92:95]
	s_and_saveexec_b64 s[14:15], s[36:37]
	ds_write_b32 v192, v161
	s_or_b64 exec, exec, s[14:15]
	s_waitcnt lgkmcnt(0)
	s_barrier
; #define LAS __attribute__((address_space(3)))
; #define MFMA32(a, b, c) __builtin_amdgcn_mfma_f32_32x32x16_bf16((a), (b), (c), 0, 0, 0)
; DI int crow(int reg, int h) { return (reg & 3) + 8 * (reg >> 2) + 4 * h; }
; DI void ssm_prompt_unit(LAS unsigned char* lds, int unit, int tid, int l, const bf16_t* U, const bf16_t* mats_l, const float* lam16_l, bf16_t* Z, float* outr_l, float* outi_l) {
;     ...
;         for (int ks = 0; ks < 16; ++ks) {
;             const bf16x8 bf = bfr[ks];
; #pragma unroll
;             for (int mi = 0; mi < 2; ++mi) { const bf16x8 af = *(const LAS bf16x8*)(lds + ((mt0 + mi) * 32 + l32) * UP_PITCH + (16 * ks + 8 * h) * 2); acc[mi] = MFMA32(af, bf, acc[mi]); }
;         }
; #pragma unroll
;         for (int mi = 0; mi < 2; ++mi)
; #pragma unroll
;             for (int i = 0; i < 16; ++i) *(LAS float*)(lds + SH_OFF + ((mt0 + mi) * 32 + crow(i, h) + 1) * UP_PITCH + (nt * 32 + l32) * 4) = acc[mi][i];
;     }
;     bf16x8 kfr[16];
;     {
;         const bf16_t* kp = mats + (size_t)(wave * 32 + l32) * 256 + 8 * h;
; #pragma unroll
;         for (int ks = 0; ks < 16; ++ks) kfr[ks] = *(const bf16x8*)(kp + 16 * ks);
;     }
;     __syncthreads();
;     if (wave == 0) {
;         int lane; asm volatile("v_mbcnt_lo_u32_b32 %0, -1, 0\n\tv_mbcnt_hi_u32_b32 %0, -1, %0" : "=v"(lane));
;         const float lr = lam16_l[(g * 64 + lane) * 2], li = lam16_l[(g * 64 + lane) * 2 + 1];
	ds_read_b128 v[200:203], v193
	ds_read_b128 v[204:207], v194
	ds_read_b128 v[208:211], v193 offset:32
	ds_read_b128 v[212:215], v194 offset:32
	ds_read_b128 v[216:219], v193 offset:64
	ds_read_b128 v[220:223], v194 offset:64
	ds_read_b128 v[224:227], v193 offset:96
	ds_read_b128 v[234:237], v194 offset:96
	s_waitcnt vmcnt(1) lgkmcnt(7)
	v_mfma_f32_32x32x16_bf16 v[16:31], v[200:203], v[0:3], 0
	ds_read_b128 v[200:203], v193 offset:128
	s_waitcnt lgkmcnt(7)
	v_mfma_f32_32x32x16_bf16 v[0:15], v[204:207], v[0:3], 0
	ds_read_b128 v[204:207], v194 offset:128
	s_waitcnt lgkmcnt(7)
	v_mfma_f32_32x32x16_bf16 v[16:31], v[208:211], v[88:91], v[16:31]
	ds_read_b128 v[208:211], v193 offset:160
	s_waitcnt lgkmcnt(7)
	v_mfma_f32_32x32x16_bf16 v[0:15], v[212:215], v[88:91], v[0:15]
	ds_read_b128 v[212:215], v194 offset:160
	s_waitcnt lgkmcnt(7)
	v_mfma_f32_32x32x16_bf16 v[16:31], v[216:219], v[84:87], v[16:31]
	ds_read_b128 v[216:219], v193 offset:192
	s_waitcnt lgkmcnt(7)
	v_mfma_f32_32x32x16_bf16 v[0:15], v[220:223], v[84:87], v[0:15]
	ds_read_b128 v[220:223], v194 offset:192
	s_waitcnt lgkmcnt(7)
	v_mfma_f32_32x32x16_bf16 v[16:31], v[224:227], v[80:83], v[16:31]
	ds_read_b128 v[224:227], v193 offset:224
	s_waitcnt lgkmcnt(7)
	v_mfma_f32_32x32x16_bf16 v[0:15], v[234:237], v[80:83], v[0:15]
	ds_read_b128 v[234:237], v194 offset:224
	s_waitcnt lgkmcnt(7)
	v_mfma_f32_32x32x16_bf16 v[16:31], v[200:203], v[76:79], v[16:31]
	ds_read_b128 v[200:203], v193 offset:256
	s_waitcnt lgkmcnt(7)
	v_mfma_f32_32x32x16_bf16 v[0:15], v[204:207], v[76:79], v[0:15]
	ds_read_b128 v[204:207], v194 offset:256
	s_waitcnt lgkmcnt(7)
	v_mfma_f32_32x32x16_bf16 v[16:31], v[208:211], v[72:75], v[16:31]
	ds_read_b128 v[208:211], v193 offset:288
	s_waitcnt lgkmcnt(7)
	v_mfma_f32_32x32x16_bf16 v[0:15], v[212:215], v[72:75], v[0:15]
	ds_read_b128 v[212:215], v194 offset:288
	s_waitcnt lgkmcnt(7)
	v_mfma_f32_32x32x16_bf16 v[16:31], v[216:219], v[68:71], v[16:31]
	ds_read_b128 v[216:219], v193 offset:320
	s_waitcnt lgkmcnt(7)
	v_mfma_f32_32x32x16_bf16 v[0:15], v[220:223], v[68:71], v[0:15]
	ds_read_b128 v[220:223], v194 offset:320
	s_waitcnt lgkmcnt(7)
	v_mfma_f32_32x32x16_bf16 v[16:31], v[224:227], v[64:67], v[16:31]
	ds_read_b128 v[224:227], v193 offset:352
	s_waitcnt lgkmcnt(7)
	v_mfma_f32_32x32x16_bf16 v[0:15], v[234:237], v[64:67], v[0:15]
	ds_read_b128 v[234:237], v194 offset:352
	s_waitcnt lgkmcnt(7)
	v_mfma_f32_32x32x16_bf16 v[16:31], v[200:203], v[60:63], v[16:31]
	ds_read_b128 v[200:203], v193 offset:384
	s_waitcnt lgkmcnt(7)
	v_mfma_f32_32x32x16_bf16 v[0:15], v[204:207], v[60:63], v[0:15]
	ds_read_b128 v[204:207], v194 offset:384
	s_waitcnt lgkmcnt(7)
	v_mfma_f32_32x32x16_bf16 v[16:31], v[208:211], v[56:59], v[16:31]
	ds_read_b128 v[208:211], v193 offset:416
	s_waitcnt lgkmcnt(7)
	v_mfma_f32_32x32x16_bf16 v[0:15], v[212:215], v[56:59], v[0:15]
	ds_read_b128 v[212:215], v194 offset:416
	s_waitcnt lgkmcnt(7)
	v_mfma_f32_32x32x16_bf16 v[16:31], v[216:219], v[52:55], v[16:31]
	ds_read_b128 v[216:219], v193 offset:448
	s_waitcnt lgkmcnt(7)
	v_mfma_f32_32x32x16_bf16 v[0:15], v[220:223], v[52:55], v[0:15]
	ds_read_b128 v[220:223], v194 offset:448
	s_waitcnt lgkmcnt(7)
	v_mfma_f32_32x32x16_bf16 v[16:31], v[224:227], v[44:47], v[16:31]
	ds_read_b128 v[224:227], v193 offset:480
	s_waitcnt lgkmcnt(7)
	v_mfma_f32_32x32x16_bf16 v[0:15], v[234:237], v[44:47], v[0:15]
	ds_read_b128 v[234:237], v194 offset:480
	s_waitcnt lgkmcnt(7)
	v_mfma_f32_32x32x16_bf16 v[16:31], v[200:203], v[40:43], v[16:31]
	s_waitcnt lgkmcnt(6)
	v_mfma_f32_32x32x16_bf16 v[0:15], v[204:207], v[40:43], v[0:15]
	s_waitcnt lgkmcnt(5)
	v_mfma_f32_32x32x16_bf16 v[16:31], v[208:211], v[36:39], v[16:31]
	s_waitcnt lgkmcnt(4)
	v_mfma_f32_32x32x16_bf16 v[0:15], v[212:215], v[36:39], v[0:15]
	s_waitcnt lgkmcnt(3)
	v_mfma_f32_32x32x16_bf16 v[16:31], v[216:219], v[32:35], v[16:31]
	s_waitcnt lgkmcnt(2)
	v_mfma_f32_32x32x16_bf16 v[0:15], v[220:223], v[32:35], v[0:15]
	s_waitcnt vmcnt(0) lgkmcnt(1)
	v_mfma_f32_32x32x16_bf16 v[16:31], v[224:227], v[48:51], v[16:31]
	s_waitcnt lgkmcnt(0)
	v_mfma_f32_32x32x16_bf16 v[0:15], v[234:237], v[48:51], v[0:15]
	v_add_u32_e32 v32, 0x200, v195
	s_nop 7
	ds_write2_b32 v32, v16, v17 offset0:4 offset1:136
	v_add_u32_e32 v16, 0x600, v195
	ds_write2_b32 v16, v18, v19 offset0:12 offset1:144
	v_add_u32_e32 v16, 0x1200, v195
	ds_write2_b32 v16, v20, v21 offset0:36 offset1:168
	v_add_u32_e32 v16, 0x1600, v195
	ds_write2_b32 v16, v22, v23 offset0:44 offset1:176
	v_add_u32_e32 v16, 0x2200, v195
	ds_write2_b32 v16, v24, v25 offset0:68 offset1:200
	v_add_u32_e32 v16, 0x2600, v195
	ds_write2_b32 v16, v26, v27 offset0:76 offset1:208
	v_add_u32_e32 v16, 0x3200, v195
	ds_write2_b32 v16, v28, v29 offset0:100 offset1:232
	v_add_u32_e32 v16, 0x3600, v195
	ds_write2_b32 v16, v30, v31 offset0:108 offset1:240
	v_add_u32_e32 v16, 0x200, v196
	ds_write2_b32 v16, v0, v1 offset0:4 offset1:136
	v_add_u32_e32 v0, 0x600, v196
	ds_write2_b32 v0, v2, v3 offset0:12 offset1:144
	v_add_u32_e32 v0, 0x1200, v196
	ds_write2_b32 v0, v4, v5 offset0:36 offset1:168
	v_add_u32_e32 v0, 0x1600, v196
	ds_write2_b32 v0, v6, v7 offset0:44 offset1:176
	v_add_u32_e32 v0, 0x2200, v196
	ds_write2_b32 v0, v8, v9 offset0:68 offset1:200
	v_add_u32_e32 v0, 0x2600, v196
	ds_write2_b32 v0, v10, v11 offset0:76 offset1:208
	v_add_u32_e32 v0, 0x3200, v196
	ds_write2_b32 v0, v12, v13 offset0:100 offset1:232
	v_add_u32_e32 v0, 0x3600, v196
	ds_write2_b32 v0, v14, v15 offset0:108 offset1:240
	v_lshl_add_u64 v[0:1], s[52:53], 0, v[166:167]
	v_lshl_add_u64 v[4:5], v[0:1], 0, v[160:161]
	global_load_dwordx4 v[0:3], v[4:5], off
	global_load_dwordx4 v[120:123], v[4:5], off offset:32
	global_load_dwordx4 v[116:119], v[4:5], off offset:64
	global_load_dwordx4 v[112:115], v[4:5], off offset:96
	global_load_dwordx4 v[108:111], v[4:5], off offset:128
	global_load_dwordx4 v[104:107], v[4:5], off offset:160
	global_load_dwordx4 v[100:103], v[4:5], off offset:192
	global_load_dwordx4 v[96:99], v[4:5], off offset:224
	global_load_dwordx4 v[92:95], v[4:5], off offset:256
	global_load_dwordx4 v[88:91], v[4:5], off offset:288
	global_load_dwordx4 v[84:87], v[4:5], off offset:320
	global_load_dwordx4 v[80:83], v[4:5], off offset:352
	global_load_dwordx4 v[76:79], v[4:5], off offset:384
	global_load_dwordx4 v[72:75], v[4:5], off offset:416
	global_load_dwordx4 v[68:71], v[4:5], off offset:448
	global_load_dwordx4 v[64:67], v[4:5], off offset:480
	s_waitcnt lgkmcnt(0)
	s_barrier
	s_and_saveexec_b64 s[54:55], s[38:39]
	s_cbranch_execz .LBB0_405
	v_mbcnt_lo_u32_b32 v4, -1, 0
	v_mbcnt_hi_u32_b32 v4, -1, v4
	v_mov_b32_e32 v10, 0
	v_lshlrev_b32_e32 v5, 1, v4
	v_lshl_add_u32 v6, s6, 7, v5
	v_ashrrev_i32_e32 v7, 31, v6
	v_lshl_add_u64 v[6:7], v[6:7], 2, s[0:1]
	global_load_dwordx2 v[6:7], v[6:7], off
	s_mov_b32 s7, -8
	s_mov_b32 s14, 0
	v_lshlrev_b32_e32 v12, 2, v4
	v_mov_b32_e32 v11, v10
	s_waitcnt vmcnt(0)
	v_pk_mov_b32 v[8:9], v[6:7], v[6:7] op_sel:[1,0]

; #define LAS __attribute__((address_space(3)))
; #define MFMA32(a, b, c) __builtin_amdgcn_mfma_f32_32x32x16_bf16((a), (b), (c), 0, 0, 0)
; DI void ssm_prompt_unit(LAS unsigned char* lds, int unit, int tid, int l, const bf16_t* U, const bf16_t* mats_l, const float* lam16_l, bf16_t* Z, float* outr_l, float* outi_l) {
;     ...
;         bf16x8 cfr[8];
;         {
;             const bf16_t* cp = mats + 98304 + (size_t)(wave * 32 + l32) * 128 + 8 * h;
; #pragma unroll
;             for (int ks = 0; ks < 8; ++ks) cfr[ks] = *(const bf16x8*)(cp + 16 * ks);
;         }
;         f32x16 acc[4];
; #pragma unroll
;         for (int mt = 0; mt < 4; ++mt)
; #pragma unroll
;             for (int i = 0; i < 16; ++i) acc[mt][i] = 0.f;
; #pragma unroll
;         for (int ks = 0; ks < 16; ++ks) {
;             const bf16x8 af = kfr[ks];
; #pragma unroll
;             for (int mt = 0; mt < 4; ++mt) { const bf16x8 bf = *(const LAS bf16x8*)(lds + (mt * 32 + l32) * UP_PITCH + (16 * ks + 8 * h) * 2); acc[mt] = MFMA32(af, bf, acc[mt]); }
;         }
.LBB0_405:
	s_or_b64 exec, exec, s[54:55]
	v_lshl_add_u64 v[4:5], s[52:53], 0, v[168:169]
	s_lshl_b32 s14, s6, 4
	v_lshl_add_u64 v[4:5], v[4:5], 0, v[160:161]
	s_mov_b64 s[6:7], 0x30000
	v_lshl_add_u64 v[6:7], v[4:5], 0, s[6:7]
	v_add_co_u32_e32 v4, vcc, 0x30000, v4
	s_waitcnt lgkmcnt(0)
	s_nop 0
	v_addc_co_u32_e32 v5, vcc, 0, v5, vcc
	s_barrier
	global_load_dwordx4 v[152:155], v[4:5], off
	global_load_dwordx4 v[148:151], v[6:7], off offset:32
	global_load_dwordx4 v[144:147], v[6:7], off offset:64
	global_load_dwordx4 v[140:143], v[6:7], off offset:96
	global_load_dwordx4 v[136:139], v[6:7], off offset:128
	global_load_dwordx4 v[132:135], v[6:7], off offset:160
	global_load_dwordx4 v[128:131], v[6:7], off offset:192
	global_load_dwordx4 v[124:127], v[6:7], off offset:224
	ds_read_b128 v[200:203], v182
	ds_read_b128 v[204:207], v182 offset:32
	ds_read_b128 v[208:211], v182 offset:16896
	ds_read_b128 v[212:215], v182 offset:16928
	ds_read_b128 v[216:219], v182 offset:33792
	ds_read_b128 v[220:223], v182 offset:33824
	ds_read_b128 v[224:227], v182 offset:50688
	ds_read_b128 v[234:237], v182 offset:50720
	s_waitcnt vmcnt(23) lgkmcnt(7)
	v_mfma_f32_32x32x16_bf16 v[48:63], v[0:3], v[200:203], 0
	ds_read_b128 v[200:203], v182 offset:64
	s_waitcnt vmcnt(22) lgkmcnt(7)
	v_mfma_f32_32x32x16_bf16 v[48:63], v[120:123], v[204:207], v[48:63]
	ds_read_b128 v[204:207], v182 offset:16960
	s_waitcnt lgkmcnt(7)
	v_mfma_f32_32x32x16_bf16 v[32:47], v[0:3], v[208:211], 0
	ds_read_b128 v[208:211], v182 offset:33856
	s_waitcnt lgkmcnt(7)
	v_mfma_f32_32x32x16_bf16 v[32:47], v[120:123], v[212:215], v[32:47]
	ds_read_b128 v[212:215], v182 offset:50752
	s_waitcnt lgkmcnt(7)
	v_mfma_f32_32x32x16_bf16 v[16:31], v[0:3], v[216:219], 0
	ds_read_b128 v[216:219], v182 offset:96
	s_waitcnt lgkmcnt(7)
	v_mfma_f32_32x32x16_bf16 v[16:31], v[120:123], v[220:223], v[16:31]
	ds_read_b128 v[220:223], v182 offset:16992
	s_waitcnt lgkmcnt(7)
	v_mfma_f32_32x32x16_bf16 v[0:15], v[0:3], v[224:227], 0
	ds_read_b128 v[224:227], v182 offset:33888
	s_waitcnt lgkmcnt(7)
	v_mfma_f32_32x32x16_bf16 v[0:15], v[120:123], v[234:237], v[0:15]
	ds_read_b128 v[234:237], v182 offset:50784
	s_waitcnt vmcnt(21) lgkmcnt(7)
	v_mfma_f32_32x32x16_bf16 v[48:63], v[116:119], v[200:203], v[48:63]
	ds_read_b128 v[200:203], v182 offset:128
	s_waitcnt lgkmcnt(7)
	v_mfma_f32_32x32x16_bf16 v[32:47], v[116:119], v[204:207], v[32:47]
	ds_read_b128 v[204:207], v182 offset:17024
	s_waitcnt lgkmcnt(7)
	v_mfma_f32_32x32x16_bf16 v[16:31], v[116:119], v[208:211], v[16:31]
	ds_read_b128 v[208:211], v182 offset:33920
	s_waitcnt lgkmcnt(7)
	v_mfma_f32_32x32x16_bf16 v[0:15], v[116:119], v[212:215], v[0:15]
	ds_read_b128 v[212:215], v182 offset:50816
	s_waitcnt vmcnt(20) lgkmcnt(7)
	v_mfma_f32_32x32x16_bf16 v[48:63], v[112:115], v[216:219], v[48:63]
	ds_read_b128 v[216:219], v182 offset:160
	s_waitcnt lgkmcnt(7)
	v_mfma_f32_32x32x16_bf16 v[32:47], v[112:115], v[220:223], v[32:47]
	ds_read_b128 v[220:223], v182 offset:17056
	s_waitcnt lgkmcnt(7)
	v_mfma_f32_32x32x16_bf16 v[16:31], v[112:115], v[224:227], v[16:31]
	ds_read_b128 v[224:227], v182 offset:33952
	s_waitcnt lgkmcnt(7)
	v_mfma_f32_32x32x16_bf16 v[0:15], v[112:115], v[234:237], v[0:15]
	ds_read_b128 v[234:237], v182 offset:50848
	s_waitcnt vmcnt(19) lgkmcnt(7)
	v_mfma_f32_32x32x16_bf16 v[48:63], v[108:111], v[200:203], v[48:63]
	ds_read_b128 v[200:203], v182 offset:192
	s_waitcnt lgkmcnt(7)
	v_mfma_f32_32x32x16_bf16 v[32:47], v[108:111], v[204:207], v[32:47]
	ds_read_b128 v[204:207], v182 offset:17088
	s_waitcnt lgkmcnt(7)
	v_mfma_f32_32x32x16_bf16 v[16:31], v[108:111], v[208:211], v[16:31]
	ds_read_b128 v[208:211], v182 offset:33984
	s_waitcnt lgkmcnt(7)
	v_mfma_f32_32x32x16_bf16 v[0:15], v[108:111], v[212:215], v[0:15]
	ds_read_b128 v[212:215], v182 offset:50880
	s_waitcnt vmcnt(18) lgkmcnt(7)
	v_mfma_f32_32x32x16_bf16 v[48:63], v[104:107], v[216:219], v[48:63]
	ds_read_b128 v[216:219], v182 offset:224
	s_waitcnt lgkmcnt(7)
	v_mfma_f32_32x32x16_bf16 v[32:47], v[104:107], v[220:223], v[32:47]
	ds_read_b128 v[220:223], v182 offset:17120
	s_waitcnt lgkmcnt(7)
	v_mfma_f32_32x32x16_bf16 v[16:31], v[104:107], v[224:227], v[16:31]
	ds_read_b128 v[224:227], v182 offset:34016
	s_waitcnt lgkmcnt(7)
	v_mfma_f32_32x32x16_bf16 v[0:15], v[104:107], v[234:237], v[0:15]
	ds_read_b128 v[234:237], v182 offset:50912
	s_waitcnt vmcnt(17) lgkmcnt(7)
	v_mfma_f32_32x32x16_bf16 v[48:63], v[100:103], v[200:203], v[48:63]
	ds_read_b128 v[200:203], v182 offset:256
	s_waitcnt lgkmcnt(7)
	v_mfma_f32_32x32x16_bf16 v[32:47], v[100:103], v[204:207], v[32:47]
	ds_read_b128 v[204:207], v182 offset:17152
	s_waitcnt lgkmcnt(7)
	v_mfma_f32_32x32x16_bf16 v[16:31], v[100:103], v[208:211], v[16:31]
	ds_read_b128 v[208:211], v182 offset:34048
	s_waitcnt lgkmcnt(7)
	v_mfma_f32_32x32x16_bf16 v[0:15], v[100:103], v[212:215], v[0:15]
	ds_read_b128 v[212:215], v182 offset:50944
	s_waitcnt vmcnt(16) lgkmcnt(7)
	v_mfma_f32_32x32x16_bf16 v[48:63], v[96:99], v[216:219], v[48:63]
	ds_read_b128 v[216:219], v182 offset:288
	s_waitcnt lgkmcnt(7)
	v_mfma_f32_32x32x16_bf16 v[32:47], v[96:99], v[220:223], v[32:47]
	ds_read_b128 v[220:223], v182 offset:17184
	s_waitcnt lgkmcnt(7)
	v_mfma_f32_32x32x16_bf16 v[16:31], v[96:99], v[224:227], v[16:31]
	ds_read_b128 v[224:227], v182 offset:34080
	s_waitcnt lgkmcnt(7)
	v_mfma_f32_32x32x16_bf16 v[0:15], v[96:99], v[234:237], v[0:15]
	ds_read_b128 v[234:237], v182 offset:50976
	s_waitcnt vmcnt(15) lgkmcnt(7)
	v_mfma_f32_32x32x16_bf16 v[48:63], v[92:95], v[200:203], v[48:63]
	ds_read_b128 v[200:203], v182 offset:320
	s_waitcnt lgkmcnt(7)
; #define LAS __attribute__((address_space(3)))
; #define MFMA32(a, b, c) __builtin_amdgcn_mfma_f32_32x32x16_bf16((a), (b), (c), 0, 0, 0)
; DI void ssm_prompt_unit(LAS unsigned char* lds, int unit, int tid, int l, const bf16_t* U, const bf16_t* mats_l, const float* lam16_l, bf16_t* Z, float* outr_l, float* outi_l) {
;     ...
;         for (int ks = 0; ks < 16; ++ks) {
;             const bf16x8 af = kfr[ks];
; #pragma unroll
;             for (int mt = 0; mt < 4; ++mt) { const bf16x8 bf = *(const LAS bf16x8*)(lds + (mt * 32 + l32) * UP_PITCH + (16 * ks + 8 * h) * 2); acc[mt] = MFMA32(af, bf, acc[mt]); }
;         }
; #pragma unroll
;         for (int ks = 0; ks < 8; ++ks) {
;             const bf16x8 af = cfr[ks];
; #pragma unroll
;             for (int mt = 0; mt < 4; ++mt) { const bf16x8 bf = *(const LAS bf16x8*)(lds + SH_OFF + (mt * 32 + l32) * UP_PITCH + (16 * ks + 8 * h) * 2); acc[mt] = MFMA32(af, bf, acc[mt]); }
;         }
	v_mfma_f32_32x32x16_bf16 v[32:47], v[92:95], v[204:207], v[32:47]
	ds_read_b128 v[204:207], v182 offset:17216
	s_waitcnt lgkmcnt(7)
	v_mfma_f32_32x32x16_bf16 v[16:31], v[92:95], v[208:211], v[16:31]
	ds_read_b128 v[208:211], v182 offset:34112
	s_waitcnt lgkmcnt(7)
	v_mfma_f32_32x32x16_bf16 v[0:15], v[92:95], v[212:215], v[0:15]
	ds_read_b128 v[212:215], v182 offset:51008
	s_waitcnt vmcnt(14) lgkmcnt(7)
	v_mfma_f32_32x32x16_bf16 v[48:63], v[88:91], v[216:219], v[48:63]
	ds_read_b128 v[216:219], v182 offset:352
	s_waitcnt lgkmcnt(7)
	v_mfma_f32_32x32x16_bf16 v[32:47], v[88:91], v[220:223], v[32:47]
	ds_read_b128 v[220:223], v182 offset:17248
	s_waitcnt lgkmcnt(7)
	v_mfma_f32_32x32x16_bf16 v[16:31], v[88:91], v[224:227], v[16:31]
	ds_read_b128 v[224:227], v182 offset:34144
	s_waitcnt lgkmcnt(7)
	v_mfma_f32_32x32x16_bf16 v[0:15], v[88:91], v[234:237], v[0:15]
	ds_read_b128 v[234:237], v182 offset:51040
	s_waitcnt vmcnt(13) lgkmcnt(7)
	v_mfma_f32_32x32x16_bf16 v[48:63], v[84:87], v[200:203], v[48:63]
	ds_read_b128 v[200:203], v182 offset:384
	s_waitcnt lgkmcnt(7)
	v_mfma_f32_32x32x16_bf16 v[32:47], v[84:87], v[204:207], v[32:47]
	ds_read_b128 v[204:207], v182 offset:17280
	s_waitcnt lgkmcnt(7)
	v_mfma_f32_32x32x16_bf16 v[16:31], v[84:87], v[208:211], v[16:31]
	ds_read_b128 v[208:211], v182 offset:34176
	s_waitcnt lgkmcnt(7)
	v_mfma_f32_32x32x16_bf16 v[0:15], v[84:87], v[212:215], v[0:15]
	ds_read_b128 v[212:215], v182 offset:51072
	s_waitcnt vmcnt(12) lgkmcnt(7)
	v_mfma_f32_32x32x16_bf16 v[48:63], v[80:83], v[216:219], v[48:63]
	ds_read_b128 v[216:219], v182 offset:416
	s_waitcnt lgkmcnt(7)
	v_mfma_f32_32x32x16_bf16 v[32:47], v[80:83], v[220:223], v[32:47]
	ds_read_b128 v[220:223], v182 offset:17312
	s_waitcnt lgkmcnt(7)
	v_mfma_f32_32x32x16_bf16 v[16:31], v[80:83], v[224:227], v[16:31]
	ds_read_b128 v[224:227], v182 offset:34208
	s_waitcnt lgkmcnt(7)
	v_mfma_f32_32x32x16_bf16 v[0:15], v[80:83], v[234:237], v[0:15]
	ds_read_b128 v[234:237], v182 offset:51104
	s_waitcnt vmcnt(11) lgkmcnt(7)
	v_mfma_f32_32x32x16_bf16 v[48:63], v[76:79], v[200:203], v[48:63]
	ds_read_b128 v[200:203], v182 offset:448
	s_waitcnt lgkmcnt(7)
	v_mfma_f32_32x32x16_bf16 v[32:47], v[76:79], v[204:207], v[32:47]
	ds_read_b128 v[204:207], v182 offset:17344
	s_waitcnt lgkmcnt(7)
	v_mfma_f32_32x32x16_bf16 v[16:31], v[76:79], v[208:211], v[16:31]
	ds_read_b128 v[208:211], v182 offset:34240
	s_waitcnt lgkmcnt(7)
	v_mfma_f32_32x32x16_bf16 v[0:15], v[76:79], v[212:215], v[0:15]
	ds_read_b128 v[212:215], v182 offset:51136
	s_waitcnt vmcnt(10) lgkmcnt(7)
	v_mfma_f32_32x32x16_bf16 v[48:63], v[72:75], v[216:219], v[48:63]
	ds_read_b128 v[216:219], v182 offset:480
	s_waitcnt lgkmcnt(7)
	v_mfma_f32_32x32x16_bf16 v[32:47], v[72:75], v[220:223], v[32:47]
	ds_read_b128 v[220:223], v182 offset:17376
	s_waitcnt lgkmcnt(7)
	v_mfma_f32_32x32x16_bf16 v[16:31], v[72:75], v[224:227], v[16:31]
	ds_read_b128 v[224:227], v182 offset:34272
	s_waitcnt lgkmcnt(7)
	v_mfma_f32_32x32x16_bf16 v[0:15], v[72:75], v[234:237], v[0:15]
	ds_read_b128 v[234:237], v182 offset:51168
	s_waitcnt vmcnt(9) lgkmcnt(7)
	v_mfma_f32_32x32x16_bf16 v[48:63], v[68:71], v[200:203], v[48:63]
	ds_read_b128 v[200:203], v197
	s_waitcnt lgkmcnt(7)
	v_mfma_f32_32x32x16_bf16 v[32:47], v[68:71], v[204:207], v[32:47]
	ds_read_b128 v[204:207], v197 offset:16896
	s_waitcnt lgkmcnt(7)
	v_mfma_f32_32x32x16_bf16 v[16:31], v[68:71], v[208:211], v[16:31]
	ds_read_b128 v[208:211], v197 offset:33792
	s_waitcnt lgkmcnt(7)
	v_mfma_f32_32x32x16_bf16 v[0:15], v[68:71], v[212:215], v[0:15]
	ds_read_b128 v[212:215], v197 offset:50688
	s_waitcnt vmcnt(8) lgkmcnt(7)
	v_mfma_f32_32x32x16_bf16 v[48:63], v[64:67], v[216:219], v[48:63]
	ds_read_b128 v[216:219], v197 offset:16928
	s_waitcnt lgkmcnt(7)
	v_mfma_f32_32x32x16_bf16 v[32:47], v[64:67], v[220:223], v[32:47]
	ds_read_b128 v[220:223], v197 offset:33824
	s_waitcnt lgkmcnt(7)
	v_mfma_f32_32x32x16_bf16 v[16:31], v[64:67], v[224:227], v[16:31]
	ds_read_b128 v[224:227], v197 offset:32
	s_waitcnt lgkmcnt(7)
	v_mfma_f32_32x32x16_bf16 v[0:15], v[64:67], v[234:237], v[0:15]
	ds_read_b128 v[234:237], v197 offset:50720
	s_waitcnt vmcnt(7) lgkmcnt(7)
	v_mfma_f32_32x32x16_bf16 v[48:63], v[152:155], v[200:203], v[48:63]
	ds_read_b128 v[200:203], v197 offset:64
	s_waitcnt lgkmcnt(7)
	v_mfma_f32_32x32x16_bf16 v[32:47], v[152:155], v[204:207], v[32:47]
	ds_read_b128 v[204:207], v197 offset:16960
	s_waitcnt lgkmcnt(7)
	v_mfma_f32_32x32x16_bf16 v[16:31], v[152:155], v[208:211], v[16:31]
	ds_read_b128 v[208:211], v197 offset:33856
	s_waitcnt lgkmcnt(7)
	v_mfma_f32_32x32x16_bf16 v[0:15], v[152:155], v[212:215], v[0:15]
	ds_read_b128 v[212:215], v197 offset:50752
	s_waitcnt vmcnt(6) lgkmcnt(7)
	v_mfma_f32_32x32x16_bf16 v[32:47], v[148:151], v[216:219], v[32:47]
	ds_read_b128 v[216:219], v197 offset:96
	s_waitcnt lgkmcnt(7)
	v_mfma_f32_32x32x16_bf16 v[16:31], v[148:151], v[220:223], v[16:31]
	ds_read_b128 v[220:223], v197 offset:16992
	s_waitcnt lgkmcnt(7)
	v_mfma_f32_32x32x16_bf16 v[48:63], v[148:151], v[224:227], v[48:63]
	ds_read_b128 v[224:227], v197 offset:33888
	s_waitcnt lgkmcnt(7)
	v_mfma_f32_32x32x16_bf16 v[0:15], v[148:151], v[234:237], v[0:15]
	ds_read_b128 v[234:237], v197 offset:50784
	s_waitcnt vmcnt(5) lgkmcnt(7)
	v_mfma_f32_32x32x16_bf16 v[48:63], v[144:147], v[200:203], v[48:63]
	ds_read_b128 v[200:203], v197 offset:128
	s_waitcnt lgkmcnt(7)
	v_mfma_f32_32x32x16_bf16 v[32:47], v[144:147], v[204:207], v[32:47]
	ds_read_b128 v[204:207], v197 offset:17024
	s_waitcnt lgkmcnt(7)
	v_mfma_f32_32x32x16_bf16 v[16:31], v[144:147], v[208:211], v[16:31]
	ds_read_b128 v[208:211], v197 offset:33920
	s_waitcnt lgkmcnt(7)
; #define LAS __attribute__((address_space(3)))
; #define MFMA32(a, b, c) __builtin_amdgcn_mfma_f32_32x32x16_bf16((a), (b), (c), 0, 0, 0)
; DI unsigned pk2(float lo, float hi) { const f32x2 v = {lo, hi}; return __builtin_bit_cast(unsigned, __builtin_convertvector(v, bf16v2)); }
; DI void ssm_prompt_unit(LAS unsigned char* lds, int unit, int tid, int l, const bf16_t* U, const bf16_t* mats_l, const float* lam16_l, bf16_t* Z, float* outr_l, float* outi_l) {
;     ...
;         for (int ks = 0; ks < 8; ++ks) {
;             const bf16x8 af = cfr[ks];
; #pragma unroll
;             for (int mt = 0; mt < 4; ++mt) { const bf16x8 bf = *(const LAS bf16x8*)(lds + SH_OFF + (mt * 32 + l32) * UP_PITCH + (16 * ks + 8 * h) * 2); acc[mt] = MFMA32(af, bf, acc[mt]); }
;         }
;         __syncthreads();
; #pragma unroll
;         for (int mt = 0; mt < 4; ++mt)
; #pragma unroll
;             for (int g4 = 0; g4 < 4; ++g4) {
;                 const int tok = 16 * (mt * 32 + l32) + 2 * wave + (g4 >> 1), c0 = 8 * (g4 & 1) + 4 * h;
;                 u32x2 w; w.x = pk2(gelu_tanh(acc[mt][4 * g4]), gelu_tanh(acc[mt][4 * g4 + 1])); w.y = pk2(gelu_tanh(acc[mt][4 * g4 + 2]), gelu_tanh(acc[mt][4 * g4 + 3]));
;                 *(LAS u32x2*)(lds + tok * 32 + c0 * 2) = w;
	v_mfma_f32_32x32x16_bf16 v[0:15], v[144:147], v[212:215], v[0:15]
	ds_read_b128 v[212:215], v197 offset:50816
	s_waitcnt vmcnt(4) lgkmcnt(7)
	v_mfma_f32_32x32x16_bf16 v[48:63], v[140:143], v[216:219], v[48:63]
	ds_read_b128 v[216:219], v197 offset:160
	s_waitcnt lgkmcnt(7)
	v_mfma_f32_32x32x16_bf16 v[32:47], v[140:143], v[220:223], v[32:47]
	ds_read_b128 v[220:223], v197 offset:17056
	s_waitcnt lgkmcnt(7)
	v_mfma_f32_32x32x16_bf16 v[16:31], v[140:143], v[224:227], v[16:31]
	ds_read_b128 v[224:227], v197 offset:33952
	s_waitcnt lgkmcnt(7)
	v_mfma_f32_32x32x16_bf16 v[0:15], v[140:143], v[234:237], v[0:15]
	ds_read_b128 v[234:237], v197 offset:50848
	s_waitcnt vmcnt(3) lgkmcnt(7)
	v_mfma_f32_32x32x16_bf16 v[48:63], v[136:139], v[200:203], v[48:63]
	ds_read_b128 v[200:203], v197 offset:192
	s_waitcnt lgkmcnt(7)
	v_mfma_f32_32x32x16_bf16 v[32:47], v[136:139], v[204:207], v[32:47]
	ds_read_b128 v[204:207], v197 offset:17088
	s_waitcnt lgkmcnt(7)
	v_mfma_f32_32x32x16_bf16 v[16:31], v[136:139], v[208:211], v[16:31]
	ds_read_b128 v[208:211], v197 offset:33984
	s_waitcnt lgkmcnt(7)
	v_mfma_f32_32x32x16_bf16 v[0:15], v[136:139], v[212:215], v[0:15]
	ds_read_b128 v[212:215], v197 offset:50880
	s_waitcnt vmcnt(2) lgkmcnt(7)
	v_mfma_f32_32x32x16_bf16 v[48:63], v[132:135], v[216:219], v[48:63]
	ds_read_b128 v[216:219], v197 offset:224
	s_waitcnt lgkmcnt(7)
	v_mfma_f32_32x32x16_bf16 v[32:47], v[132:135], v[220:223], v[32:47]
	ds_read_b128 v[220:223], v197 offset:17120
	s_waitcnt lgkmcnt(7)
	v_mfma_f32_32x32x16_bf16 v[16:31], v[132:135], v[224:227], v[16:31]
	ds_read_b128 v[224:227], v197 offset:34016
	s_waitcnt lgkmcnt(7)
	v_mfma_f32_32x32x16_bf16 v[0:15], v[132:135], v[234:237], v[0:15]
	ds_read_b128 v[234:237], v197 offset:50912
	s_waitcnt vmcnt(1) lgkmcnt(7)
	v_mfma_f32_32x32x16_bf16 v[48:63], v[128:131], v[200:203], v[48:63]
	s_waitcnt lgkmcnt(6)
	v_mfma_f32_32x32x16_bf16 v[32:47], v[128:131], v[204:207], v[32:47]
	s_waitcnt lgkmcnt(5)
	v_mfma_f32_32x32x16_bf16 v[16:31], v[128:131], v[208:211], v[16:31]
	s_waitcnt lgkmcnt(4)
	v_mfma_f32_32x32x16_bf16 v[0:15], v[128:131], v[212:215], v[0:15]
	s_waitcnt vmcnt(0) lgkmcnt(3)
	v_mfma_f32_32x32x16_bf16 v[48:63], v[124:127], v[216:219], v[48:63]
	s_waitcnt lgkmcnt(2)
	v_mfma_f32_32x32x16_bf16 v[32:47], v[124:127], v[220:223], v[32:47]
	s_waitcnt lgkmcnt(1)
	v_mfma_f32_32x32x16_bf16 v[16:31], v[124:127], v[224:227], v[16:31]
	s_waitcnt lgkmcnt(0)
	s_barrier
	v_mfma_f32_32x32x16_bf16 v[0:15], v[124:127], v[234:237], v[0:15]
	s_nop 1
	v_mul_f32_e32 v64, 0x3d372713, v48
	v_mul_f32_e32 v65, 0x3d372713, v49
	v_mul_f32_e32 v64, v48, v64
	v_mul_f32_e32 v65, v49, v65
	v_fma_f32 v64, v48, v64, v48
	v_fma_f32 v65, v49, v65, v49
	v_mul_f32_e32 v64, 0x3f4c422a, v64
	v_mul_f32_e32 v65, 0x3f4c422a, v65
	v_add_f32_e32 v64, v64, v64
	v_add_f32_e32 v65, v65, v65
	v_mul_f32_e32 v64, 0x3fb8aa3b, v64
	v_mul_f32_e32 v65, 0x3fb8aa3b, v65
	v_exp_f32_e32 v64, v64
	v_exp_f32_e32 v65, v65
	v_pk_mul_f32 v[48:49], v[48:49], 0.5 op_sel_hi:[1,0]
	v_add_f32_e32 v64, 1.0, v64
	v_add_f32_e32 v65, 1.0, v65
	v_rcp_f32_e32 v64, v64
	v_rcp_f32_e32 v65, v65
	s_nop 0
	v_pk_fma_f32 v[64:65], v[64:65], 2.0, 1.0 op_sel_hi:[1,0,0] neg_lo:[1,0,0] neg_hi:[1,0,0]
	s_nop 0
	v_pk_add_f32 v[64:65], v[64:65], 1.0 op_sel_hi:[1,0]
	s_nop 0
	v_pk_mul_f32 v[48:49], v[48:49], v[64:65]
	s_nop 0
	v_cvt_pk_bf16_f32 v48, v48, v49
	v_mul_f32_e32 v49, 0x3d372713, v50
	v_mul_f32_e32 v49, v50, v49
	v_fma_f32 v49, v50, v49, v50
	v_mul_f32_e32 v49, 0x3f4c422a, v49
	v_add_f32_e32 v49, v49, v49
	v_mul_f32_e32 v49, 0x3fb8aa3b, v49
	v_exp_f32_e32 v49, v49
	s_nop 0
	v_add_f32_e32 v49, 1.0, v49
	v_rcp_f32_e32 v64, v49
	v_mul_f32_e32 v49, 0x3d372713, v51
	v_mul_f32_e32 v49, v51, v49
	v_fma_f32 v49, v51, v49, v51
	v_mul_f32_e32 v49, 0x3f4c422a, v49
	v_add_f32_e32 v49, v49, v49
	v_mul_f32_e32 v49, 0x3fb8aa3b, v49
	v_exp_f32_e32 v49, v49
	v_pk_mul_f32 v[50:51], v[50:51], 0.5 op_sel_hi:[1,0]
	v_add_f32_e32 v49, 1.0, v49
	v_rcp_f32_e32 v65, v49
	s_nop 0
	v_pk_fma_f32 v[64:65], v[64:65], 2.0, 1.0 op_sel_hi:[1,0,0] neg_lo:[1,0,0] neg_hi:[1,0,0]
	s_nop 0
	v_pk_add_f32 v[64:65], v[64:65], 1.0 op_sel_hi:[1,0]
	s_nop 0
	v_pk_mul_f32 v[50:51], v[50:51], v[64:65]
	s_nop 0
	v_cvt_pk_bf16_f32 v49, v50, v51
	v_mul_f32_e32 v50, 0x3d372713, v52
	v_mul_f32_e32 v51, 0x3d372713, v53
	v_mul_f32_e32 v50, v52, v50
	v_mul_f32_e32 v51, v53, v51
	v_fma_f32 v50, v52, v50, v52
	v_fma_f32 v51, v53, v51, v53
	v_mul_f32_e32 v50, 0x3f4c422a, v50
	v_mul_f32_e32 v51, 0x3f4c422a, v51
	v_add_f32_e32 v50, v50, v50
	v_add_f32_e32 v51, v51, v51
	v_mul_f32_e32 v50, 0x3fb8aa3b, v50
	v_mul_f32_e32 v51, 0x3fb8aa3b, v51
	v_exp_f32_e32 v50, v50
	v_exp_f32_e32 v51, v51
	v_pk_mul_f32 v[52:53], v[52:53], 0.5 op_sel_hi:[1,0]
	v_add_f32_e32 v50, 1.0, v50
	v_add_f32_e32 v51, 1.0, v51
	v_rcp_f32_e32 v50, v50
	v_rcp_f32_e32 v51, v51
	s_nop 0
	v_pk_fma_f32 v[50:51], v[50:51], 2.0, 1.0 op_sel_hi:[1,0,0] neg_lo:[1,0,0] neg_hi:[1,0,0]
	s_nop 0
	v_pk_add_f32 v[50:51], v[50:51], 1.0 op_sel_hi:[1,0]
	s_nop 0
	v_pk_mul_f32 v[50:51], v[52:53], v[50:51]
	s_nop 0
	v_cvt_pk_bf16_f32 v50, v50, v51
	v_mul_f32_e32 v51, 0x3d372713, v54
	v_mul_f32_e32 v51, v54, v51
	v_fma_f32 v51, v54, v51, v54
	v_mul_f32_e32 v51, 0x3f4c422a, v51
	v_add_f32_e32 v51, v51, v51
	v_mul_f32_e32 v51, 0x3fb8aa3b, v51
	v_exp_f32_e32 v51, v51
	s_nop 0
	v_add_f32_e32 v51, 1.0, v51
	v_rcp_f32_e32 v52, v51
	v_mul_f32_e32 v51, 0x3d372713, v55
	v_mul_f32_e32 v51, v55, v51
	v_fma_f32 v51, v55, v51, v55
	v_mul_f32_e32 v51, 0x3f4c422a, v51
	v_add_f32_e32 v51, v51, v51
	v_mul_f32_e32 v51, 0x3fb8aa3b, v51
	v_exp_f32_e32 v51, v51
	v_pk_mul_f32 v[54:55], v[54:55], 0.5 op_sel_hi:[1,0]
; #define LAS __attribute__((address_space(3)))
; DI unsigned pk2(float lo, float hi) { const f32x2 v = {lo, hi}; return __builtin_bit_cast(unsigned, __builtin_convertvector(v, bf16v2)); }
; DI float frcp(float x) { return __builtin_amdgcn_rcpf(x); }
; DI float gelu_tanh(float x) {
;     const float t = 0.7978845608028654f * (x + 0.044715f * x * x * x);
;     const float e = __expf(2.f * t);
;     const float th = 1.f - 2.f * frcp(e + 1.f);
;     return 0.5f * x * (1.f + th);
; }
; DI void ssm_prompt_unit(LAS unsigned char* lds, int unit, int tid, int l, const bf16_t* U, const bf16_t* mats_l, const float* lam16_l, bf16_t* Z, float* outr_l, float* outi_l) {
;     ...
; #pragma unroll
;         for (int mt = 0; mt < 4; ++mt)
; #pragma unroll
;             for (int g4 = 0; g4 < 4; ++g4) {
;                 const int tok = 16 * (mt * 32 + l32) + 2 * wave + (g4 >> 1), c0 = 8 * (g4 & 1) + 4 * h;
;                 u32x2 w; w.x = pk2(gelu_tanh(acc[mt][4 * g4]), gelu_tanh(acc[mt][4 * g4 + 1])); w.y = pk2(gelu_tanh(acc[mt][4 * g4 + 2]), gelu_tanh(acc[mt][4 * g4 + 3]));
;                 *(LAS u32x2*)(lds + tok * 32 + c0 * 2) = w;
;             }
	v_add_f32_e32 v51, 1.0, v51
	v_rcp_f32_e32 v53, v51
	s_nop 0
	v_pk_fma_f32 v[52:53], v[52:53], 2.0, 1.0 op_sel_hi:[1,0,0] neg_lo:[1,0,0] neg_hi:[1,0,0]
	s_nop 0
	v_pk_add_f32 v[52:53], v[52:53], 1.0 op_sel_hi:[1,0]
	s_nop 0
	v_pk_mul_f32 v[52:53], v[54:55], v[52:53]
	v_pk_mul_f32 v[54:55], v[62:63], 0.5 op_sel_hi:[1,0]
	v_cvt_pk_bf16_f32 v51, v52, v53
	ds_write2_b64 v198, v[48:49], v[50:51] offset1:2
	v_mul_f32_e32 v48, 0x3d372713, v56
	v_mul_f32_e32 v49, 0x3d372713, v57
	v_mul_f32_e32 v48, v56, v48
	v_mul_f32_e32 v49, v57, v49
	v_fma_f32 v48, v56, v48, v56
	v_fma_f32 v49, v57, v49, v57
	v_mul_f32_e32 v48, 0x3f4c422a, v48
	v_mul_f32_e32 v49, 0x3f4c422a, v49
	v_add_f32_e32 v48, v48, v48
	v_add_f32_e32 v49, v49, v49
	v_mul_f32_e32 v48, 0x3fb8aa3b, v48
	v_mul_f32_e32 v49, 0x3fb8aa3b, v49
	v_exp_f32_e32 v48, v48
	v_exp_f32_e32 v49, v49
	v_pk_mul_f32 v[50:51], v[56:57], 0.5 op_sel_hi:[1,0]
	v_pk_mul_f32 v[52:53], v[58:59], 0.5 op_sel_hi:[1,0]
	v_add_f32_e32 v48, 1.0, v48
	v_add_f32_e32 v49, 1.0, v49
	v_rcp_f32_e32 v48, v48
	v_rcp_f32_e32 v49, v49
	s_nop 0
	v_pk_fma_f32 v[48:49], v[48:49], 2.0, 1.0 op_sel_hi:[1,0,0] neg_lo:[1,0,0] neg_hi:[1,0,0]
	s_nop 0
	v_pk_add_f32 v[48:49], v[48:49], 1.0 op_sel_hi:[1,0]
	s_nop 0
	v_pk_mul_f32 v[48:49], v[50:51], v[48:49]
	s_nop 0
	v_cvt_pk_bf16_f32 v48, v48, v49
	v_mul_f32_e32 v49, 0x3d372713, v58
	v_mul_f32_e32 v49, v58, v49
	v_fma_f32 v49, v58, v49, v58
	v_mul_f32_e32 v49, 0x3f4c422a, v49
	v_add_f32_e32 v49, v49, v49
	v_mul_f32_e32 v49, 0x3fb8aa3b, v49
	v_exp_f32_e32 v49, v49
	s_nop 0
	v_add_f32_e32 v49, 1.0, v49
	v_rcp_f32_e32 v50, v49
	v_mul_f32_e32 v49, 0x3d372713, v59
	v_mul_f32_e32 v49, v59, v49
	v_fma_f32 v49, v59, v49, v59
	v_mul_f32_e32 v49, 0x3f4c422a, v49
	v_add_f32_e32 v49, v49, v49
	v_mul_f32_e32 v49, 0x3fb8aa3b, v49
	v_exp_f32_e32 v49, v49
	s_nop 0
	v_add_f32_e32 v49, 1.0, v49
	v_rcp_f32_e32 v51, v49
	s_nop 0
	v_pk_fma_f32 v[50:51], v[50:51], 2.0, 1.0 op_sel_hi:[1,0,0] neg_lo:[1,0,0] neg_hi:[1,0,0]
	s_nop 0
	v_pk_add_f32 v[50:51], v[50:51], 1.0 op_sel_hi:[1,0]
	s_nop 0
	v_pk_mul_f32 v[50:51], v[52:53], v[50:51]
	v_pk_mul_f32 v[52:53], v[60:61], 0.5 op_sel_hi:[1,0]
	v_cvt_pk_bf16_f32 v49, v50, v51
	v_mul_f32_e32 v50, 0x3d372713, v60
	v_mul_f32_e32 v51, 0x3d372713, v61
	v_mul_f32_e32 v50, v60, v50
	v_mul_f32_e32 v51, v61, v51
	v_fma_f32 v50, v60, v50, v60
	v_fma_f32 v51, v61, v51, v61
	v_mul_f32_e32 v50, 0x3f4c422a, v50
	v_mul_f32_e32 v51, 0x3f4c422a, v51
	v_add_f32_e32 v50, v50, v50
	v_add_f32_e32 v51, v51, v51
	v_mul_f32_e32 v50, 0x3fb8aa3b, v50
	v_mul_f32_e32 v51, 0x3fb8aa3b, v51
	v_exp_f32_e32 v50, v50
	v_exp_f32_e32 v51, v51
	v_add_f32_e32 v50, 1.0, v50
	v_add_f32_e32 v51, 1.0, v51
	v_rcp_f32_e32 v50, v50
	v_rcp_f32_e32 v51, v51
	s_nop 0
	v_pk_fma_f32 v[50:51], v[50:51], 2.0, 1.0 op_sel_hi:[1,0,0] neg_lo:[1,0,0] neg_hi:[1,0,0]
	s_nop 0
	v_pk_add_f32 v[50:51], v[50:51], 1.0 op_sel_hi:[1,0]
	s_nop 0
	v_pk_mul_f32 v[50:51], v[52:53], v[50:51]
	s_nop 0
	v_cvt_pk_bf16_f32 v50, v50, v51
	v_mul_f32_e32 v51, 0x3d372713, v62
	v_mul_f32_e32 v51, v62, v51
	v_fma_f32 v51, v62, v51, v62
	v_mul_f32_e32 v51, 0x3f4c422a, v51
	v_add_f32_e32 v51, v51, v51
	v_mul_f32_e32 v51, 0x3fb8aa3b, v51
	v_exp_f32_e32 v51, v51
	s_nop 0
	v_add_f32_e32 v51, 1.0, v51
	v_rcp_f32_e32 v52, v51
	v_mul_f32_e32 v51, 0x3d372713, v63
	v_mul_f32_e32 v51, v63, v51
	v_fma_f32 v51, v63, v51, v63
	v_mul_f32_e32 v51, 0x3f4c422a, v51
	v_add_f32_e32 v51, v51, v51
	v_mul_f32_e32 v51, 0x3fb8aa3b, v51
	v_exp_f32_e32 v51, v51
	s_nop 0
	v_add_f32_e32 v51, 1.0, v51
	v_rcp_f32_e32 v53, v51
	s_nop 0
	v_pk_fma_f32 v[52:53], v[52:53], 2.0, 1.0 op_sel_hi:[1,0,0] neg_lo:[1,0,0] neg_hi:[1,0,0]
	s_nop 0
	v_pk_add_f32 v[52:53], v[52:53], 1.0 op_sel_hi:[1,0]
	s_nop 0
	v_pk_mul_f32 v[52:53], v[54:55], v[52:53]
	s_nop 0
	v_cvt_pk_bf16_f32 v51, v52, v53
	ds_write2_b64 v198, v[48:49], v[50:51] offset0:4 offset1:6
	v_mul_f32_e32 v48, 0x3d372713, v32
	v_mul_f32_e32 v49, 0x3d372713, v33
	v_mul_f32_e32 v48, v32, v48
	v_mul_f32_e32 v49, v33, v49
	v_fma_f32 v48, v32, v48, v32
	v_fma_f32 v49, v33, v49, v33
	v_mul_f32_e32 v48, 0x3f4c422a, v48
	v_mul_f32_e32 v49, 0x3f4c422a, v49
	v_add_f32_e32 v48, v48, v48
	v_add_f32_e32 v49, v49, v49
	v_mul_f32_e32 v48, 0x3fb8aa3b, v48
	v_mul_f32_e32 v49, 0x3fb8aa3b, v49
	v_exp_f32_e32 v48, v48
	v_exp_f32_e32 v49, v49
	v_pk_mul_f32 v[32:33], v[32:33], 0.5 op_sel_hi:[1,0]
	v_add_f32_e32 v48, 1.0, v48
	v_add_f32_e32 v49, 1.0, v49
	v_rcp_f32_e32 v48, v48
	v_rcp_f32_e32 v49, v49
	s_nop 0
	v_pk_fma_f32 v[48:49], v[48:49], 2.0, 1.0 op_sel_hi:[1,0,0] neg_lo:[1,0,0] neg_hi:[1,0,0]
	s_nop 0
	v_pk_add_f32 v[48:49], v[48:49], 1.0 op_sel_hi:[1,0]
	s_nop 0
	v_pk_mul_f32 v[32:33], v[32:33], v[48:49]
	s_nop 0
	v_cvt_pk_bf16_f32 v32, v32, v33
	v_mul_f32_e32 v33, 0x3d372713, v34
	v_mul_f32_e32 v33, v34, v33
	v_fma_f32 v33, v34, v33, v34
	v_mul_f32_e32 v33, 0x3f4c422a, v33
	v_add_f32_e32 v33, v33, v33
	v_mul_f32_e32 v33, 0x3fb8aa3b, v33
	v_exp_f32_e32 v33, v33
	s_nop 0
	v_add_f32_e32 v33, 1.0, v33
	v_rcp_f32_e32 v48, v33
	v_mul_f32_e32 v33, 0x3d372713, v35
	v_mul_f32_e32 v33, v35, v33
	v_fma_f32 v33, v35, v33, v35
	v_mul_f32_e32 v33, 0x3f4c422a, v33
	v_add_f32_e32 v33, v33, v33
	v_mul_f32_e32 v33, 0x3fb8aa3b, v33
	v_exp_f32_e32 v33, v33
	v_pk_mul_f32 v[34:35], v[34:35], 0.5 op_sel_hi:[1,0]
	v_add_f32_e32 v33, 1.0, v33
	v_rcp_f32_e32 v49, v33
	s_nop 0
	v_pk_fma_f32 v[48:49], v[48:49], 2.0, 1.0 op_sel_hi:[1,0,0] neg_lo:[1,0,0] neg_hi:[1,0,0]
	s_nop 0
	v_pk_add_f32 v[48:49], v[48:49], 1.0 op_sel_hi:[1,0]
	s_nop 0
	v_pk_mul_f32 v[34:35], v[34:35], v[48:49]
	v_add_u32_e32 v48, 0x4200, v198
	v_cvt_pk_bf16_f32 v33, v34, v35
	v_mul_f32_e32 v34, 0x3d372713, v36
; #define LAS __attribute__((address_space(3)))
; DI unsigned pk2(float lo, float hi) { const f32x2 v = {lo, hi}; return __builtin_bit_cast(unsigned, __builtin_convertvector(v, bf16v2)); }
; DI float frcp(float x) { return __builtin_amdgcn_rcpf(x); }
; DI float gelu_tanh(float x) {
;     const float t = 0.7978845608028654f * (x + 0.044715f * x * x * x);
;     const float e = __expf(2.f * t);
;     const float th = 1.f - 2.f * frcp(e + 1.f);
;     return 0.5f * x * (1.f + th);
; }
; DI void ssm_prompt_unit(LAS unsigned char* lds, int unit, int tid, int l, const bf16_t* U, const bf16_t* mats_l, const float* lam16_l, bf16_t* Z, float* outr_l, float* outi_l) {
;     ...
; #pragma unroll
;         for (int mt = 0; mt < 4; ++mt)
; #pragma unroll
;             for (int g4 = 0; g4 < 4; ++g4) {
;                 const int tok = 16 * (mt * 32 + l32) + 2 * wave + (g4 >> 1), c0 = 8 * (g4 & 1) + 4 * h;
;                 u32x2 w; w.x = pk2(gelu_tanh(acc[mt][4 * g4]), gelu_tanh(acc[mt][4 * g4 + 1])); w.y = pk2(gelu_tanh(acc[mt][4 * g4 + 2]), gelu_tanh(acc[mt][4 * g4 + 3]));
;                 *(LAS u32x2*)(lds + tok * 32 + c0 * 2) = w;
;             }
	v_mul_f32_e32 v35, 0x3d372713, v37
	v_mul_f32_e32 v34, v36, v34
	v_mul_f32_e32 v35, v37, v35
	v_fma_f32 v34, v36, v34, v36
	v_fma_f32 v35, v37, v35, v37
	v_mul_f32_e32 v34, 0x3f4c422a, v34
	v_mul_f32_e32 v35, 0x3f4c422a, v35
	v_add_f32_e32 v34, v34, v34
	v_add_f32_e32 v35, v35, v35
	v_mul_f32_e32 v34, 0x3fb8aa3b, v34
	v_mul_f32_e32 v35, 0x3fb8aa3b, v35
	v_exp_f32_e32 v34, v34
	v_exp_f32_e32 v35, v35
	v_pk_mul_f32 v[36:37], v[36:37], 0.5 op_sel_hi:[1,0]
	v_add_f32_e32 v34, 1.0, v34
	v_add_f32_e32 v35, 1.0, v35
	v_rcp_f32_e32 v34, v34
	v_rcp_f32_e32 v35, v35
	s_nop 0
	v_pk_fma_f32 v[34:35], v[34:35], 2.0, 1.0 op_sel_hi:[1,0,0] neg_lo:[1,0,0] neg_hi:[1,0,0]
	s_nop 0
	v_pk_add_f32 v[34:35], v[34:35], 1.0 op_sel_hi:[1,0]
	s_nop 0
	v_pk_mul_f32 v[34:35], v[36:37], v[34:35]
	s_nop 0
	v_cvt_pk_bf16_f32 v34, v34, v35
	v_mul_f32_e32 v35, 0x3d372713, v38
	v_mul_f32_e32 v35, v38, v35
	v_fma_f32 v35, v38, v35, v38
	v_mul_f32_e32 v35, 0x3f4c422a, v35
	v_add_f32_e32 v35, v35, v35
	v_mul_f32_e32 v35, 0x3fb8aa3b, v35
	v_exp_f32_e32 v35, v35
	s_nop 0
	v_add_f32_e32 v35, 1.0, v35
	v_rcp_f32_e32 v36, v35
	v_mul_f32_e32 v35, 0x3d372713, v39
	v_mul_f32_e32 v35, v39, v35
	v_fma_f32 v35, v39, v35, v39
	v_mul_f32_e32 v35, 0x3f4c422a, v35
	v_add_f32_e32 v35, v35, v35
	v_mul_f32_e32 v35, 0x3fb8aa3b, v35
	v_exp_f32_e32 v35, v35
	v_pk_mul_f32 v[38:39], v[38:39], 0.5 op_sel_hi:[1,0]
	v_add_f32_e32 v35, 1.0, v35
	v_rcp_f32_e32 v37, v35
	s_nop 0
	v_pk_fma_f32 v[36:37], v[36:37], 2.0, 1.0 op_sel_hi:[1,0,0] neg_lo:[1,0,0] neg_hi:[1,0,0]
	s_nop 0
	v_pk_add_f32 v[36:37], v[36:37], 1.0 op_sel_hi:[1,0]
	s_nop 0
	v_pk_mul_f32 v[36:37], v[38:39], v[36:37]
	v_pk_mul_f32 v[38:39], v[46:47], 0.5 op_sel_hi:[1,0]
	v_cvt_pk_bf16_f32 v35, v36, v37
	ds_write2_b64 v48, v[32:33], v[34:35] offset1:2
	v_mul_f32_e32 v32, 0x3d372713, v40
	v_mul_f32_e32 v33, 0x3d372713, v41
	v_mul_f32_e32 v32, v40, v32
	v_mul_f32_e32 v33, v41, v33
	v_fma_f32 v32, v40, v32, v40
	v_fma_f32 v33, v41, v33, v41
	v_mul_f32_e32 v32, 0x3f4c422a, v32
	v_mul_f32_e32 v33, 0x3f4c422a, v33
	v_add_f32_e32 v32, v32, v32
	v_add_f32_e32 v33, v33, v33
	v_mul_f32_e32 v32, 0x3fb8aa3b, v32
	v_mul_f32_e32 v33, 0x3fb8aa3b, v33
	v_exp_f32_e32 v32, v32
	v_exp_f32_e32 v33, v33
	v_pk_mul_f32 v[34:35], v[40:41], 0.5 op_sel_hi:[1,0]
	v_pk_mul_f32 v[36:37], v[42:43], 0.5 op_sel_hi:[1,0]
	v_add_f32_e32 v32, 1.0, v32
	v_add_f32_e32 v33, 1.0, v33
	v_rcp_f32_e32 v32, v32
	v_rcp_f32_e32 v33, v33
	s_nop 0
	v_pk_fma_f32 v[32:33], v[32:33], 2.0, 1.0 op_sel_hi:[1,0,0] neg_lo:[1,0,0] neg_hi:[1,0,0]
	s_nop 0
	v_pk_add_f32 v[32:33], v[32:33], 1.0 op_sel_hi:[1,0]
	s_nop 0
	v_pk_mul_f32 v[32:33], v[34:35], v[32:33]
	s_nop 0
	v_cvt_pk_bf16_f32 v32, v32, v33
	v_mul_f32_e32 v33, 0x3d372713, v42
	v_mul_f32_e32 v33, v42, v33
	v_fma_f32 v33, v42, v33, v42
	v_mul_f32_e32 v33, 0x3f4c422a, v33
	v_add_f32_e32 v33, v33, v33
	v_mul_f32_e32 v33, 0x3fb8aa3b, v33
	v_exp_f32_e32 v33, v33
	s_nop 0
	v_add_f32_e32 v33, 1.0, v33
	v_rcp_f32_e32 v34, v33
	v_mul_f32_e32 v33, 0x3d372713, v43
	v_mul_f32_e32 v33, v43, v33
	v_fma_f32 v33, v43, v33, v43
	v_mul_f32_e32 v33, 0x3f4c422a, v33
	v_add_f32_e32 v33, v33, v33
	v_mul_f32_e32 v33, 0x3fb8aa3b, v33
	v_exp_f32_e32 v33, v33
	s_nop 0
	v_add_f32_e32 v33, 1.0, v33
	v_rcp_f32_e32 v35, v33
	s_nop 0
	v_pk_fma_f32 v[34:35], v[34:35], 2.0, 1.0 op_sel_hi:[1,0,0] neg_lo:[1,0,0] neg_hi:[1,0,0]
	s_nop 0
	v_pk_add_f32 v[34:35], v[34:35], 1.0 op_sel_hi:[1,0]
	s_nop 0
	v_pk_mul_f32 v[34:35], v[36:37], v[34:35]
	v_pk_mul_f32 v[36:37], v[44:45], 0.5 op_sel_hi:[1,0]
	v_cvt_pk_bf16_f32 v33, v34, v35
	v_mul_f32_e32 v34, 0x3d372713, v44
	v_mul_f32_e32 v35, 0x3d372713, v45
	v_mul_f32_e32 v34, v44, v34
	v_mul_f32_e32 v35, v45, v35
	v_fma_f32 v34, v44, v34, v44
	v_fma_f32 v35, v45, v35, v45
	v_mul_f32_e32 v34, 0x3f4c422a, v34
	v_mul_f32_e32 v35, 0x3f4c422a, v35
	v_add_f32_e32 v34, v34, v34
	v_add_f32_e32 v35, v35, v35
	v_mul_f32_e32 v34, 0x3fb8aa3b, v34
	v_mul_f32_e32 v35, 0x3fb8aa3b, v35
	v_exp_f32_e32 v34, v34
	v_exp_f32_e32 v35, v35
	v_add_f32_e32 v34, 1.0, v34
	v_add_f32_e32 v35, 1.0, v35
	v_rcp_f32_e32 v34, v34
	v_rcp_f32_e32 v35, v35
	s_nop 0
	v_pk_fma_f32 v[34:35], v[34:35], 2.0, 1.0 op_sel_hi:[1,0,0] neg_lo:[1,0,0] neg_hi:[1,0,0]
	s_nop 0
	v_pk_add_f32 v[34:35], v[34:35], 1.0 op_sel_hi:[1,0]
	s_nop 0
	v_pk_mul_f32 v[34:35], v[36:37], v[34:35]
	s_nop 0
	v_cvt_pk_bf16_f32 v34, v34, v35
	v_mul_f32_e32 v35, 0x3d372713, v46
	v_mul_f32_e32 v35, v46, v35
	v_fma_f32 v35, v46, v35, v46
	v_mul_f32_e32 v35, 0x3f4c422a, v35
	v_add_f32_e32 v35, v35, v35
	v_mul_f32_e32 v35, 0x3fb8aa3b, v35
	v_exp_f32_e32 v35, v35
	s_nop 0
	v_add_f32_e32 v35, 1.0, v35
	v_rcp_f32_e32 v36, v35
	v_mul_f32_e32 v35, 0x3d372713, v47
	v_mul_f32_e32 v35, v47, v35
	v_fma_f32 v35, v47, v35, v47
	v_mul_f32_e32 v35, 0x3f4c422a, v35
	v_add_f32_e32 v35, v35, v35
	v_mul_f32_e32 v35, 0x3fb8aa3b, v35
	v_exp_f32_e32 v35, v35
	s_nop 0
	v_add_f32_e32 v35, 1.0, v35
	v_rcp_f32_e32 v37, v35
	s_nop 0
	v_pk_fma_f32 v[36:37], v[36:37], 2.0, 1.0 op_sel_hi:[1,0,0] neg_lo:[1,0,0] neg_hi:[1,0,0]
	s_nop 0
	v_pk_add_f32 v[36:37], v[36:37], 1.0 op_sel_hi:[1,0]
	s_nop 0
	v_pk_mul_f32 v[36:37], v[38:39], v[36:37]
	s_nop 0
	v_cvt_pk_bf16_f32 v35, v36, v37
	ds_write2_b64 v48, v[32:33], v[34:35] offset0:4 offset1:6
	v_mul_f32_e32 v32, 0x3d372713, v16
	v_mul_f32_e32 v33, 0x3d372713, v17
	v_mul_f32_e32 v32, v16, v32
	v_mul_f32_e32 v33, v17, v33
	v_fma_f32 v32, v16, v32, v16
	v_fma_f32 v33, v17, v33, v17
	v_mul_f32_e32 v32, 0x3f4c422a, v32
	v_mul_f32_e32 v33, 0x3f4c422a, v33
	v_add_f32_e32 v32, v32, v32
	v_add_f32_e32 v33, v33, v33
	v_mul_f32_e32 v32, 0x3fb8aa3b, v32
	v_mul_f32_e32 v33, 0x3fb8aa3b, v33
; #define LAS __attribute__((address_space(3)))
; DI unsigned pk2(float lo, float hi) { const f32x2 v = {lo, hi}; return __builtin_bit_cast(unsigned, __builtin_convertvector(v, bf16v2)); }
; DI float frcp(float x) { return __builtin_amdgcn_rcpf(x); }
; DI float gelu_tanh(float x) {
;     const float t = 0.7978845608028654f * (x + 0.044715f * x * x * x);
;     const float e = __expf(2.f * t);
;     const float th = 1.f - 2.f * frcp(e + 1.f);
;     return 0.5f * x * (1.f + th);
; }
; DI void ssm_prompt_unit(LAS unsigned char* lds, int unit, int tid, int l, const bf16_t* U, const bf16_t* mats_l, const float* lam16_l, bf16_t* Z, float* outr_l, float* outi_l) {
;     ...
; #pragma unroll
;         for (int mt = 0; mt < 4; ++mt)
; #pragma unroll
;             for (int g4 = 0; g4 < 4; ++g4) {
;                 const int tok = 16 * (mt * 32 + l32) + 2 * wave + (g4 >> 1), c0 = 8 * (g4 & 1) + 4 * h;
;                 u32x2 w; w.x = pk2(gelu_tanh(acc[mt][4 * g4]), gelu_tanh(acc[mt][4 * g4 + 1])); w.y = pk2(gelu_tanh(acc[mt][4 * g4 + 2]), gelu_tanh(acc[mt][4 * g4 + 3]));
;                 *(LAS u32x2*)(lds + tok * 32 + c0 * 2) = w;
;             }
	v_exp_f32_e32 v32, v32
	v_exp_f32_e32 v33, v33
	v_pk_mul_f32 v[16:17], v[16:17], 0.5 op_sel_hi:[1,0]
	v_add_f32_e32 v32, 1.0, v32
	v_add_f32_e32 v33, 1.0, v33
	v_rcp_f32_e32 v32, v32
	v_rcp_f32_e32 v33, v33
	s_nop 0
	v_pk_fma_f32 v[32:33], v[32:33], 2.0, 1.0 op_sel_hi:[1,0,0] neg_lo:[1,0,0] neg_hi:[1,0,0]
	s_nop 0
	v_pk_add_f32 v[32:33], v[32:33], 1.0 op_sel_hi:[1,0]
	s_nop 0
	v_pk_mul_f32 v[16:17], v[16:17], v[32:33]
	s_nop 0
	v_cvt_pk_bf16_f32 v16, v16, v17
	v_mul_f32_e32 v17, 0x3d372713, v18
	v_mul_f32_e32 v17, v18, v17
	v_fma_f32 v17, v18, v17, v18
	v_mul_f32_e32 v17, 0x3f4c422a, v17
	v_add_f32_e32 v17, v17, v17
	v_mul_f32_e32 v17, 0x3fb8aa3b, v17
	v_exp_f32_e32 v17, v17
	s_nop 0
	v_add_f32_e32 v17, 1.0, v17
	v_rcp_f32_e32 v32, v17
	v_mul_f32_e32 v17, 0x3d372713, v19
	v_mul_f32_e32 v17, v19, v17
	v_fma_f32 v17, v19, v17, v19
	v_mul_f32_e32 v17, 0x3f4c422a, v17
	v_add_f32_e32 v17, v17, v17
	v_mul_f32_e32 v17, 0x3fb8aa3b, v17
	v_exp_f32_e32 v17, v17
	v_pk_mul_f32 v[18:19], v[18:19], 0.5 op_sel_hi:[1,0]
	v_add_f32_e32 v17, 1.0, v17
	v_rcp_f32_e32 v33, v17
	s_nop 0
	v_pk_fma_f32 v[32:33], v[32:33], 2.0, 1.0 op_sel_hi:[1,0,0] neg_lo:[1,0,0] neg_hi:[1,0,0]
	s_nop 0
	v_pk_add_f32 v[32:33], v[32:33], 1.0 op_sel_hi:[1,0]
	s_nop 0
	v_pk_mul_f32 v[18:19], v[18:19], v[32:33]
	v_add_u32_e32 v32, 0x8400, v198
	v_cvt_pk_bf16_f32 v17, v18, v19
	v_mul_f32_e32 v18, 0x3d372713, v20
	v_mul_f32_e32 v19, 0x3d372713, v21
	v_mul_f32_e32 v18, v20, v18
	v_mul_f32_e32 v19, v21, v19
	v_fma_f32 v18, v20, v18, v20
	v_fma_f32 v19, v21, v19, v21
	v_mul_f32_e32 v18, 0x3f4c422a, v18
	v_mul_f32_e32 v19, 0x3f4c422a, v19
	v_add_f32_e32 v18, v18, v18
	v_add_f32_e32 v19, v19, v19
	v_mul_f32_e32 v18, 0x3fb8aa3b, v18
	v_mul_f32_e32 v19, 0x3fb8aa3b, v19
	v_exp_f32_e32 v18, v18
	v_exp_f32_e32 v19, v19
	v_pk_mul_f32 v[20:21], v[20:21], 0.5 op_sel_hi:[1,0]
	v_add_f32_e32 v18, 1.0, v18
	v_add_f32_e32 v19, 1.0, v19
	v_rcp_f32_e32 v18, v18
	v_rcp_f32_e32 v19, v19
	s_nop 0
	v_pk_fma_f32 v[18:19], v[18:19], 2.0, 1.0 op_sel_hi:[1,0,0] neg_lo:[1,0,0] neg_hi:[1,0,0]
	s_nop 0
	v_pk_add_f32 v[18:19], v[18:19], 1.0 op_sel_hi:[1,0]
	s_nop 0
	v_pk_mul_f32 v[18:19], v[20:21], v[18:19]
	s_nop 0
	v_cvt_pk_bf16_f32 v18, v18, v19
	v_mul_f32_e32 v19, 0x3d372713, v22
	v_mul_f32_e32 v19, v22, v19
	v_fma_f32 v19, v22, v19, v22
	v_mul_f32_e32 v19, 0x3f4c422a, v19
	v_add_f32_e32 v19, v19, v19
	v_mul_f32_e32 v19, 0x3fb8aa3b, v19
	v_exp_f32_e32 v19, v19
	s_nop 0
	v_add_f32_e32 v19, 1.0, v19
	v_rcp_f32_e32 v20, v19
	v_mul_f32_e32 v19, 0x3d372713, v23
	v_mul_f32_e32 v19, v23, v19
	v_fma_f32 v19, v23, v19, v23
	v_mul_f32_e32 v19, 0x3f4c422a, v19
	v_add_f32_e32 v19, v19, v19
	v_mul_f32_e32 v19, 0x3fb8aa3b, v19
	v_exp_f32_e32 v19, v19
	v_pk_mul_f32 v[22:23], v[22:23], 0.5 op_sel_hi:[1,0]
	v_add_f32_e32 v19, 1.0, v19
	v_rcp_f32_e32 v21, v19
	s_nop 0
	v_pk_fma_f32 v[20:21], v[20:21], 2.0, 1.0 op_sel_hi:[1,0,0] neg_lo:[1,0,0] neg_hi:[1,0,0]
	s_nop 0
	v_pk_add_f32 v[20:21], v[20:21], 1.0 op_sel_hi:[1,0]
	s_nop 0
	v_pk_mul_f32 v[20:21], v[22:23], v[20:21]
	v_pk_mul_f32 v[22:23], v[30:31], 0.5 op_sel_hi:[1,0]
	v_cvt_pk_bf16_f32 v19, v20, v21
	ds_write2_b64 v32, v[16:17], v[18:19] offset1:2
	v_mul_f32_e32 v16, 0x3d372713, v24
	v_mul_f32_e32 v17, 0x3d372713, v25
	v_mul_f32_e32 v16, v24, v16
	v_mul_f32_e32 v17, v25, v17
	v_fma_f32 v16, v24, v16, v24
	v_fma_f32 v17, v25, v17, v25
	v_mul_f32_e32 v16, 0x3f4c422a, v16
	v_mul_f32_e32 v17, 0x3f4c422a, v17
	v_add_f32_e32 v16, v16, v16
	v_add_f32_e32 v17, v17, v17
	v_mul_f32_e32 v16, 0x3fb8aa3b, v16
	v_mul_f32_e32 v17, 0x3fb8aa3b, v17
	v_exp_f32_e32 v16, v16
	v_exp_f32_e32 v17, v17
	v_pk_mul_f32 v[18:19], v[24:25], 0.5 op_sel_hi:[1,0]
	v_pk_mul_f32 v[20:21], v[26:27], 0.5 op_sel_hi:[1,0]
	v_add_f32_e32 v16, 1.0, v16
	v_add_f32_e32 v17, 1.0, v17
	v_rcp_f32_e32 v16, v16
	v_rcp_f32_e32 v17, v17
	s_nop 0
	v_pk_fma_f32 v[16:17], v[16:17], 2.0, 1.0 op_sel_hi:[1,0,0] neg_lo:[1,0,0] neg_hi:[1,0,0]
	s_nop 0
	v_pk_add_f32 v[16:17], v[16:17], 1.0 op_sel_hi:[1,0]
	s_nop 0
	v_pk_mul_f32 v[16:17], v[18:19], v[16:17]
	s_nop 0
	v_cvt_pk_bf16_f32 v16, v16, v17
	v_mul_f32_e32 v17, 0x3d372713, v26
	v_mul_f32_e32 v17, v26, v17
	v_fma_f32 v17, v26, v17, v26
	v_mul_f32_e32 v17, 0x3f4c422a, v17
	v_add_f32_e32 v17, v17, v17
	v_mul_f32_e32 v17, 0x3fb8aa3b, v17
	v_exp_f32_e32 v17, v17
	s_nop 0
	v_add_f32_e32 v17, 1.0, v17
	v_rcp_f32_e32 v18, v17
	v_mul_f32_e32 v17, 0x3d372713, v27
	v_mul_f32_e32 v17, v27, v17
	v_fma_f32 v17, v27, v17, v27
	v_mul_f32_e32 v17, 0x3f4c422a, v17
	v_add_f32_e32 v17, v17, v17
	v_mul_f32_e32 v17, 0x3fb8aa3b, v17
	v_exp_f32_e32 v17, v17
	s_nop 0
	v_add_f32_e32 v17, 1.0, v17
	v_rcp_f32_e32 v19, v17
	s_nop 0
	v_pk_fma_f32 v[18:19], v[18:19], 2.0, 1.0 op_sel_hi:[1,0,0] neg_lo:[1,0,0] neg_hi:[1,0,0]
	s_nop 0
	v_pk_add_f32 v[18:19], v[18:19], 1.0 op_sel_hi:[1,0]
	s_nop 0
	v_pk_mul_f32 v[18:19], v[20:21], v[18:19]
	v_pk_mul_f32 v[20:21], v[28:29], 0.5 op_sel_hi:[1,0]
	v_cvt_pk_bf16_f32 v17, v18, v19
	v_mul_f32_e32 v18, 0x3d372713, v28
	v_mul_f32_e32 v19, 0x3d372713, v29
	v_mul_f32_e32 v18, v28, v18
	v_mul_f32_e32 v19, v29, v19
	v_fma_f32 v18, v28, v18, v28
	v_fma_f32 v19, v29, v19, v29
	v_mul_f32_e32 v18, 0x3f4c422a, v18
	v_mul_f32_e32 v19, 0x3f4c422a, v19
	v_add_f32_e32 v18, v18, v18
	v_add_f32_e32 v19, v19, v19
	v_mul_f32_e32 v18, 0x3fb8aa3b, v18
	v_mul_f32_e32 v19, 0x3fb8aa3b, v19
	v_exp_f32_e32 v18, v18
	v_exp_f32_e32 v19, v19
	v_add_f32_e32 v18, 1.0, v18
	v_add_f32_e32 v19, 1.0, v19
	v_rcp_f32_e32 v18, v18
	v_rcp_f32_e32 v19, v19
	s_nop 0
	v_pk_fma_f32 v[18:19], v[18:19], 2.0, 1.0 op_sel_hi:[1,0,0] neg_lo:[1,0,0] neg_hi:[1,0,0]
	s_nop 0
	v_pk_add_f32 v[18:19], v[18:19], 1.0 op_sel_hi:[1,0]
; #define LAS __attribute__((address_space(3)))
; DI unsigned pk2(float lo, float hi) { const f32x2 v = {lo, hi}; return __builtin_bit_cast(unsigned, __builtin_convertvector(v, bf16v2)); }
; DI float frcp(float x) { return __builtin_amdgcn_rcpf(x); }
; DI float gelu_tanh(float x) {
;     const float t = 0.7978845608028654f * (x + 0.044715f * x * x * x);
;     const float e = __expf(2.f * t);
;     const float th = 1.f - 2.f * frcp(e + 1.f);
;     return 0.5f * x * (1.f + th);
; }
; DI void ssm_prompt_unit(LAS unsigned char* lds, int unit, int tid, int l, const bf16_t* U, const bf16_t* mats_l, const float* lam16_l, bf16_t* Z, float* outr_l, float* outi_l) {
;     ...
; #pragma unroll
;         for (int mt = 0; mt < 4; ++mt)
; #pragma unroll
;             for (int g4 = 0; g4 < 4; ++g4) {
;                 const int tok = 16 * (mt * 32 + l32) + 2 * wave + (g4 >> 1), c0 = 8 * (g4 & 1) + 4 * h;
;                 u32x2 w; w.x = pk2(gelu_tanh(acc[mt][4 * g4]), gelu_tanh(acc[mt][4 * g4 + 1])); w.y = pk2(gelu_tanh(acc[mt][4 * g4 + 2]), gelu_tanh(acc[mt][4 * g4 + 3]));
;                 *(LAS u32x2*)(lds + tok * 32 + c0 * 2) = w;
;             }
	s_nop 0
	v_pk_mul_f32 v[18:19], v[20:21], v[18:19]
	s_nop 0
	v_cvt_pk_bf16_f32 v18, v18, v19
	v_mul_f32_e32 v19, 0x3d372713, v30
	v_mul_f32_e32 v19, v30, v19
	v_fma_f32 v19, v30, v19, v30
	v_mul_f32_e32 v19, 0x3f4c422a, v19
	v_add_f32_e32 v19, v19, v19
	v_mul_f32_e32 v19, 0x3fb8aa3b, v19
	v_exp_f32_e32 v19, v19
	s_nop 0
	v_add_f32_e32 v19, 1.0, v19
	v_rcp_f32_e32 v20, v19
	v_mul_f32_e32 v19, 0x3d372713, v31
	v_mul_f32_e32 v19, v31, v19
	v_fma_f32 v19, v31, v19, v31
	v_mul_f32_e32 v19, 0x3f4c422a, v19
	v_add_f32_e32 v19, v19, v19
	v_mul_f32_e32 v19, 0x3fb8aa3b, v19
	v_exp_f32_e32 v19, v19
	s_nop 0
	v_add_f32_e32 v19, 1.0, v19
	v_rcp_f32_e32 v21, v19
	s_nop 0
	v_pk_fma_f32 v[20:21], v[20:21], 2.0, 1.0 op_sel_hi:[1,0,0] neg_lo:[1,0,0] neg_hi:[1,0,0]
	s_nop 0
	v_pk_add_f32 v[20:21], v[20:21], 1.0 op_sel_hi:[1,0]
	s_nop 0
	v_pk_mul_f32 v[20:21], v[22:23], v[20:21]
	s_nop 0
	v_cvt_pk_bf16_f32 v19, v20, v21
	ds_write2_b64 v32, v[16:17], v[18:19] offset0:4 offset1:6
	v_mul_f32_e32 v16, 0x3d372713, v0
	v_mul_f32_e32 v17, 0x3d372713, v1
	v_mul_f32_e32 v16, v0, v16
	v_mul_f32_e32 v17, v1, v17
	v_fma_f32 v16, v0, v16, v0
	v_fma_f32 v17, v1, v17, v1
	v_mul_f32_e32 v16, 0x3f4c422a, v16
	v_mul_f32_e32 v17, 0x3f4c422a, v17
	v_add_f32_e32 v16, v16, v16
	v_add_f32_e32 v17, v17, v17
	v_mul_f32_e32 v16, 0x3fb8aa3b, v16
	v_mul_f32_e32 v17, 0x3fb8aa3b, v17
	v_exp_f32_e32 v16, v16
	v_exp_f32_e32 v17, v17
	v_pk_mul_f32 v[0:1], v[0:1], 0.5 op_sel_hi:[1,0]
	v_add_f32_e32 v16, 1.0, v16
	v_add_f32_e32 v17, 1.0, v17
	v_rcp_f32_e32 v16, v16
	v_rcp_f32_e32 v17, v17
	s_nop 0
	v_pk_fma_f32 v[16:17], v[16:17], 2.0, 1.0 op_sel_hi:[1,0,0] neg_lo:[1,0,0] neg_hi:[1,0,0]
	s_nop 0
	v_pk_add_f32 v[16:17], v[16:17], 1.0 op_sel_hi:[1,0]
	s_nop 0
	v_pk_mul_f32 v[0:1], v[0:1], v[16:17]
	s_nop 0
	v_cvt_pk_bf16_f32 v0, v0, v1
	v_mul_f32_e32 v1, 0x3d372713, v2
	v_mul_f32_e32 v1, v2, v1
	v_fma_f32 v1, v2, v1, v2
	v_mul_f32_e32 v1, 0x3f4c422a, v1
	v_add_f32_e32 v1, v1, v1
	v_mul_f32_e32 v1, 0x3fb8aa3b, v1
	v_exp_f32_e32 v1, v1
	s_nop 0
	v_add_f32_e32 v1, 1.0, v1
	v_rcp_f32_e32 v16, v1
	v_mul_f32_e32 v1, 0x3d372713, v3
	v_mul_f32_e32 v1, v3, v1
	v_fma_f32 v1, v3, v1, v3
	v_mul_f32_e32 v1, 0x3f4c422a, v1
	v_add_f32_e32 v1, v1, v1
	v_mul_f32_e32 v1, 0x3fb8aa3b, v1
	v_exp_f32_e32 v1, v1
	v_pk_mul_f32 v[2:3], v[2:3], 0.5 op_sel_hi:[1,0]
	v_add_f32_e32 v1, 1.0, v1
	v_rcp_f32_e32 v17, v1
	s_nop 0
	v_pk_fma_f32 v[16:17], v[16:17], 2.0, 1.0 op_sel_hi:[1,0,0] neg_lo:[1,0,0] neg_hi:[1,0,0]
	s_nop 0
	v_pk_add_f32 v[16:17], v[16:17], 1.0 op_sel_hi:[1,0]
	s_nop 0
	v_pk_mul_f32 v[2:3], v[2:3], v[16:17]
	v_add_u32_e32 v16, 0xc600, v198
	v_cvt_pk_bf16_f32 v1, v2, v3
	v_mul_f32_e32 v2, 0x3d372713, v4
	v_mul_f32_e32 v3, 0x3d372713, v5
	v_mul_f32_e32 v2, v4, v2
	v_mul_f32_e32 v3, v5, v3
	v_fma_f32 v2, v4, v2, v4
	v_fma_f32 v3, v5, v3, v5
	v_mul_f32_e32 v2, 0x3f4c422a, v2
	v_mul_f32_e32 v3, 0x3f4c422a, v3
	v_add_f32_e32 v2, v2, v2
	v_add_f32_e32 v3, v3, v3
	v_mul_f32_e32 v2, 0x3fb8aa3b, v2
	v_mul_f32_e32 v3, 0x3fb8aa3b, v3
	v_exp_f32_e32 v2, v2
	v_exp_f32_e32 v3, v3
	v_pk_mul_f32 v[4:5], v[4:5], 0.5 op_sel_hi:[1,0]
	v_add_f32_e32 v2, 1.0, v2
	v_add_f32_e32 v3, 1.0, v3
	v_rcp_f32_e32 v2, v2
	v_rcp_f32_e32 v3, v3
	s_nop 0
	v_pk_fma_f32 v[2:3], v[2:3], 2.0, 1.0 op_sel_hi:[1,0,0] neg_lo:[1,0,0] neg_hi:[1,0,0]
	s_nop 0
	v_pk_add_f32 v[2:3], v[2:3], 1.0 op_sel_hi:[1,0]
	s_nop 0
	v_pk_mul_f32 v[2:3], v[4:5], v[2:3]
	s_nop 0
	v_cvt_pk_bf16_f32 v2, v2, v3
	v_mul_f32_e32 v3, 0x3d372713, v6
	v_mul_f32_e32 v3, v6, v3
	v_fma_f32 v3, v6, v3, v6
	v_mul_f32_e32 v3, 0x3f4c422a, v3
	v_add_f32_e32 v3, v3, v3
	v_mul_f32_e32 v3, 0x3fb8aa3b, v3
	v_exp_f32_e32 v3, v3
	s_nop 0
	v_add_f32_e32 v3, 1.0, v3
	v_rcp_f32_e32 v4, v3
	v_mul_f32_e32 v3, 0x3d372713, v7
	v_mul_f32_e32 v3, v7, v3
	v_fma_f32 v3, v7, v3, v7
	v_mul_f32_e32 v3, 0x3f4c422a, v3
	v_add_f32_e32 v3, v3, v3
	v_mul_f32_e32 v3, 0x3fb8aa3b, v3
; #define LAS __attribute__((address_space(3)))
; DI unsigned pk2(float lo, float hi) { const f32x2 v = {lo, hi}; return __builtin_bit_cast(unsigned, __builtin_convertvector(v, bf16v2)); }
; DI void ssm_prompt_unit(LAS unsigned char* lds, int unit, int tid, int l, const bf16_t* U, const bf16_t* mats_l, const float* lam16_l, bf16_t* Z, float* outr_l, float* outi_l) {
;     ...
; #pragma unroll
;         for (int mt = 0; mt < 4; ++mt)
; #pragma unroll
;             for (int g4 = 0; g4 < 4; ++g4) {
;                 const int tok = 16 * (mt * 32 + l32) + 2 * wave + (g4 >> 1), c0 = 8 * (g4 & 1) + 4 * h;
;                 u32x2 w; w.x = pk2(gelu_tanh(acc[mt][4 * g4]), gelu_tanh(acc[mt][4 * g4 + 1])); w.y = pk2(gelu_tanh(acc[mt][4 * g4 + 2]), gelu_tanh(acc[mt][4 * g4 + 3]));
;                 *(LAS u32x2*)(lds + tok * 32 + c0 * 2) = w;
;             }
;         __syncthreads();
;         for (int idx = tid; idx < 4096; idx += NTHREADS) {
	v_exp_f32_e32 v3, v3
	v_pk_mul_f32 v[6:7], v[6:7], 0.5 op_sel_hi:[1,0]
	v_add_f32_e32 v3, 1.0, v3
	v_rcp_f32_e32 v5, v3
	s_nop 0
	v_pk_fma_f32 v[4:5], v[4:5], 2.0, 1.0 op_sel_hi:[1,0,0] neg_lo:[1,0,0] neg_hi:[1,0,0]
	s_nop 0
	v_pk_add_f32 v[4:5], v[4:5], 1.0 op_sel_hi:[1,0]
	s_nop 0
	v_pk_mul_f32 v[4:5], v[6:7], v[4:5]
	v_pk_mul_f32 v[6:7], v[14:15], 0.5 op_sel_hi:[1,0]
	v_cvt_pk_bf16_f32 v3, v4, v5
	ds_write2_b64 v16, v[0:1], v[2:3] offset1:2
	v_mul_f32_e32 v0, 0x3d372713, v8
	v_mul_f32_e32 v1, 0x3d372713, v9
	v_mul_f32_e32 v0, v8, v0
	v_mul_f32_e32 v1, v9, v1
	v_fma_f32 v0, v8, v0, v8
	v_fma_f32 v1, v9, v1, v9
	v_mul_f32_e32 v0, 0x3f4c422a, v0
	v_mul_f32_e32 v1, 0x3f4c422a, v1
	v_add_f32_e32 v0, v0, v0
	v_add_f32_e32 v1, v1, v1
	v_mul_f32_e32 v0, 0x3fb8aa3b, v0
	v_mul_f32_e32 v1, 0x3fb8aa3b, v1
	v_exp_f32_e32 v0, v0
	v_exp_f32_e32 v1, v1
	v_pk_mul_f32 v[2:3], v[8:9], 0.5 op_sel_hi:[1,0]
	v_pk_mul_f32 v[4:5], v[10:11], 0.5 op_sel_hi:[1,0]
	v_add_f32_e32 v0, 1.0, v0
	v_add_f32_e32 v1, 1.0, v1
	v_rcp_f32_e32 v0, v0
	v_rcp_f32_e32 v1, v1
	s_nop 0
	v_pk_fma_f32 v[0:1], v[0:1], 2.0, 1.0 op_sel_hi:[1,0,0] neg_lo:[1,0,0] neg_hi:[1,0,0]
	s_nop 0
	v_pk_add_f32 v[0:1], v[0:1], 1.0 op_sel_hi:[1,0]
	s_nop 0
	v_pk_mul_f32 v[0:1], v[2:3], v[0:1]
	s_nop 0
	v_cvt_pk_bf16_f32 v0, v0, v1
	v_mul_f32_e32 v1, 0x3d372713, v10
	v_mul_f32_e32 v1, v10, v1
	v_fma_f32 v1, v10, v1, v10
	v_mul_f32_e32 v1, 0x3f4c422a, v1
	v_add_f32_e32 v1, v1, v1
	v_mul_f32_e32 v1, 0x3fb8aa3b, v1
	v_exp_f32_e32 v1, v1
	s_nop 0
	v_add_f32_e32 v1, 1.0, v1
	v_rcp_f32_e32 v2, v1
	v_mul_f32_e32 v1, 0x3d372713, v11
	v_mul_f32_e32 v1, v11, v1
	v_fma_f32 v1, v11, v1, v11
	v_mul_f32_e32 v1, 0x3f4c422a, v1
	v_add_f32_e32 v1, v1, v1
	v_mul_f32_e32 v1, 0x3fb8aa3b, v1
	v_exp_f32_e32 v1, v1
	s_nop 0
	v_add_f32_e32 v1, 1.0, v1
	v_rcp_f32_e32 v3, v1
	s_nop 0
	v_pk_fma_f32 v[2:3], v[2:3], 2.0, 1.0 op_sel_hi:[1,0,0] neg_lo:[1,0,0] neg_hi:[1,0,0]
	s_nop 0
	v_pk_add_f32 v[2:3], v[2:3], 1.0 op_sel_hi:[1,0]
	s_nop 0
	v_pk_mul_f32 v[2:3], v[4:5], v[2:3]
	v_pk_mul_f32 v[4:5], v[12:13], 0.5 op_sel_hi:[1,0]
	v_cvt_pk_bf16_f32 v1, v2, v3
	v_mul_f32_e32 v2, 0x3d372713, v12
	v_mul_f32_e32 v3, 0x3d372713, v13
	v_mul_f32_e32 v2, v12, v2
	v_mul_f32_e32 v3, v13, v3
	v_fma_f32 v2, v12, v2, v12
	v_fma_f32 v3, v13, v3, v13
	v_mul_f32_e32 v2, 0x3f4c422a, v2
	v_mul_f32_e32 v3, 0x3f4c422a, v3
	v_add_f32_e32 v2, v2, v2
	v_add_f32_e32 v3, v3, v3
	v_mul_f32_e32 v2, 0x3fb8aa3b, v2
	v_mul_f32_e32 v3, 0x3fb8aa3b, v3
	v_exp_f32_e32 v2, v2
	v_exp_f32_e32 v3, v3
	v_add_f32_e32 v2, 1.0, v2
	v_add_f32_e32 v3, 1.0, v3
	v_rcp_f32_e32 v2, v2
	v_rcp_f32_e32 v3, v3
	s_nop 0
	v_pk_fma_f32 v[2:3], v[2:3], 2.0, 1.0 op_sel_hi:[1,0,0] neg_lo:[1,0,0] neg_hi:[1,0,0]
	s_nop 0
	v_pk_add_f32 v[2:3], v[2:3], 1.0 op_sel_hi:[1,0]
	s_nop 0
	v_pk_mul_f32 v[2:3], v[4:5], v[2:3]
	s_nop 0
	v_cvt_pk_bf16_f32 v2, v2, v3
	v_mul_f32_e32 v3, 0x3d372713, v14
	v_mul_f32_e32 v3, v14, v3
	v_fma_f32 v3, v14, v3, v14
	v_mul_f32_e32 v3, 0x3f4c422a, v3
	v_add_f32_e32 v3, v3, v3
	v_mul_f32_e32 v3, 0x3fb8aa3b, v3
	v_exp_f32_e32 v3, v3
	s_nop 0
	v_add_f32_e32 v3, 1.0, v3
	v_rcp_f32_e32 v4, v3
	v_mul_f32_e32 v3, 0x3d372713, v15
	v_mul_f32_e32 v3, v15, v3
	v_fma_f32 v3, v15, v3, v15
	v_mul_f32_e32 v3, 0x3f4c422a, v3
	v_add_f32_e32 v3, v3, v3
	v_mul_f32_e32 v3, 0x3fb8aa3b, v3
	v_exp_f32_e32 v3, v3
	s_nop 0
	v_add_f32_e32 v3, 1.0, v3
	v_rcp_f32_e32 v5, v3
	s_nop 0
	v_pk_fma_f32 v[4:5], v[4:5], 2.0, 1.0 op_sel_hi:[1,0,0] neg_lo:[1,0,0] neg_hi:[1,0,0]
	s_nop 0
	v_pk_add_f32 v[4:5], v[4:5], 1.0 op_sel_hi:[1,0]
	s_nop 0
	v_pk_mul_f32 v[4:5], v[6:7], v[4:5]
	s_nop 0
	v_cvt_pk_bf16_f32 v3, v4, v5
	ds_write2_b64 v16, v[0:1], v[2:3] offset0:4 offset1:6
	s_waitcnt lgkmcnt(0)
	s_barrier
	s_and_saveexec_b64 s[52:53], s[40:41]
	s_cbranch_execz .LBB0_398
	s_lshl_b32 s18, s14, 1
	v_lshl_add_u64 v[0:1], v[170:171], 0, s[18:19]
	s_mov_b64 s[54:55], 0
	v_mov_b32_e32 v2, v157
